# phase 0 weight conversion rewritten: 3-deep register pipeline of tile loads, double-buffered LDS transpose with one barrier per tile, clamped columns instead of masks
# speedup vs baseline: 1.0303x; 1.0128x over previous
; #define LAS __attribute__((address_space(3)))
; __device__ __forceinline__ int ltid() { int t = threadIdx.x; asm volatile("" : "+v"(t)); return t; }
; __device__ __forceinline__ int lbid() { int t = blockIdx.x; asm volatile("" : "+s"(t)); return t; }
; __device__ __forceinline__ CvtTile cvt_get(const Params& p, int t) {
;     const int l = t / TILES_L; int r = t % TILES_L; unsigned char* Wl = p.ws + OFF_W + (size_t)l * SZ_WL; CvtTile c; int nT; c.mode = 0; c.gk = nullptr;
;     if (r < 576) { c.W = p.w_in + (size_t)l * DM * NPROJ; c.K = DM; c.N = NPROJ; nT = 18; c.dst = (bf16_t*)(Wl + WO_IN); c.gk = p.g_mix + l * DM; }
;     else if ((r -= 576) < 48) { c.W = p.w_q_up + (size_t)l * 512 * 1536; c.K = 512; c.N = 1536; nT = 6; c.mode = 1; c.dst = (bf16_t*)(Wl + WO_Q); }
;     else if ((r -= 48) < 32) { c.W = p.w_kv_up + (size_t)l * 256 * 2048; c.K = 256; c.N = 2048; nT = 8; c.mode = 2; c.dst = (bf16_t*)(Wl + WO_KV); }
;     else if ((r -= 32) < 256) { c.W = p.w_out + (size_t)l * DM * DM; c.K = DM; c.N = DM; nT = 8; c.dst = (bf16_t*)(Wl + WO_OUT); }
;     else if ((r -= 256) < 1024) { c.W = p.w_ff1 + (size_t)l * DM * DFF; c.K = DM; c.N = DFF; nT = 32; c.dst = (bf16_t*)(Wl + WO_1); c.gk = p.g_ffn + l * DM; }
;     else { r -= 1024; c.W = p.w_ff2 + (size_t)l * DFF * DM; c.K = DFF; c.N = DM; nT = 8; c.dst = (bf16_t*)(Wl + WO_2); }
;     c.kt = r / nT; c.nt = r % nT; return c;
; }
; __device__ __forceinline__ void cvt_load(const CvtTile& c, f32x4 (&v)[8], int tid) {
; #pragma unroll
;     for (int i = 0; i < 8; ++i) { const int k = (tid >> 6) + 8 * i, gn = c.nt * 256 + (tid & 63) * 4;
;         v[i] = (f32x4){0.f, 0.f, 0.f, 0.f};
;         if (gn < c.N) { v[i] = __builtin_nontemporal_load((const f32x4*)(c.W + (size_t)(c.kt * 64 + k) * c.N + gn)); if (c.gk) v[i] = v[i] * c.gk[c.kt * 64 + k]; } }
; }
; __device__ __forceinline__ void convert_phase(const Params& p, LAS unsigned char* lds) {
;     LAS float* T = (LAS float*)lds;
;     const int tid = ltid(), G = gridDim.x;
;     int t = lbid();
;     f32x4 v[8]; CvtTile c;
;     if (t < NLAYER * TILES_L) { c = cvt_get(p, t); cvt_load(c, v, tid); }
.LBB0_537:
	s_waitcnt lgkmcnt(0)
	v_readlane_b32 s24, v252, 0
	v_readlane_b32 s25, v252, 9
	v_readlane_b32 s30, v252, 5
	v_readlane_b32 s31, v252, 6
	v_lshrrev_b32_e32 v167, 6, v192
	v_and_b32_e32 v168, 63, v192
	v_readfirstlane_b32 s28, v167
	v_lshlrev_b32_e32 v160, 4, v168
	v_mul_u32_u24_e32 v161, 8224, v167
	v_add_u32_e32 v161, v161, v160
	v_and_b32_e32 v169, 7, v192
	v_lshrrev_b32_e32 v165, 3, v192
	v_lshlrev_b32_e32 v163, 4, v169
	v_lshlrev_b32_e32 v164, 5, v169
	v_mul_u32_u24_e32 v162, 8224, v169
	s_mov_b32 s26, s24
	s_mov_b32 s27, 0
	s_mov_b32 s29, 0
	s_cmp_lt_u32 s26, 11840
	s_cbranch_scc0 .Lcv_exit
	s_mov_b32 s0, 0
	s_cmp_ge_u32 s26, 2960
	s_addc_u32 s0, s0, 0
	s_cmp_ge_u32 s26, 5920
	s_addc_u32 s0, s0, 0
	s_cmp_ge_u32 s26, 8880
	s_addc_u32 s0, s0, 0
	s_mul_i32 s1, s0, 2960
	s_sub_u32 s1, s26, s1
	s_mul_i32 s2, s0, 0x5c80000
	s_cmp_lt_u32 s1, 576
	s_cbranch_scc0 .Lcv_p0_w_in_skip
	s_mul_i32 s3, s1, 3641
	s_lshr_b32 s3, s3, 16
	s_mul_i32 s4, s3, 18
	s_sub_u32 s4, s1, s4
	v_readlane_b32 s6, v253, 8
	v_readlane_b32 s7, v253, 9
	s_mul_i32 s5, s0, 0x22a0000
	s_mul_i32 s8, s3, 0x115000
	s_lshl_b32 s9, s4, 10
	s_add_u32 s5, s5, s8
	s_add_u32 s5, s5, s9
	s_add_u32 s34, s6, s5
	s_addc_u32 s35, s7, 0
	s_mov_b32 s36, 0x4540
	s_lshl_b32 s9, s4, 8
	s_mov_b32 s44, s9
	s_sub_u32 s10, 4428, s9
	s_lshl_b32 s37, s10, 2
	s_sub_u32 s45, 4431, s9
	s_add_u32 s5, s2, 0x0
	s_lshl_b32 s8, s3, 7
	s_add_u32 s5, s5, s8
	s_add_u32 s40, s30, s5
	s_addc_u32 s41, s31, 0
	s_mov_b32 s42, 12
	s_mov_b32 s43, 0
	v_readlane_b32 s6, v253, 6
	v_readlane_b32 s7, v253, 7
	s_lshl_b32 s5, s0, 13
	s_lshl_b32 s8, s3, 8
	s_add_u32 s5, s5, s8
	s_add_u32 s38, s6, s5
	s_addc_u32 s39, s7, 0
	s_mov_b32 s46, 1
	s_branch .Lcv_p0_done
.Lcv_p0_w_in_skip:
	s_cmp_lt_u32 s1, 624
	s_cbranch_scc0 .Lcv_p0_w_q_skip
	s_sub_u32 s1, s1, 576
	s_mul_i32 s3, s1, 10923
	s_lshr_b32 s3, s3, 16
	s_mul_i32 s4, s3, 6
	s_sub_u32 s4, s1, s4
	v_readlane_b32 s6, v253, 50
	v_readlane_b32 s7, v253, 51
	s_mul_i32 s5, s0, 0x300000
	s_mul_i32 s8, s3, 0x60000
	s_lshl_b32 s9, s4, 10
	s_add_u32 s5, s5, s8
	s_add_u32 s5, s5, s9
	s_add_u32 s34, s6, s5
	s_addc_u32 s35, s7, 0
	s_mov_b32 s36, 0x1800
	s_lshl_b32 s9, s4, 8
	s_mov_b32 s44, s9
	s_sub_u32 s10, 1532, s9
	s_lshl_b32 s37, s10, 2
	s_sub_u32 s45, 1535, s9
	s_add_u32 s5, s2, 0x1200000
	s_lshl_b32 s8, s3, 7
	s_add_u32 s5, s5, s8
	s_add_u32 s40, s30, s5
	s_addc_u32 s41, s31, 0
	s_mov_b32 s42, 10
	s_mov_b32 s43, 1
	v_readlane_b32 s38, v253, 6
	v_readlane_b32 s39, v253, 7
	s_mov_b32 s46, 0
	s_branch .Lcv_p0_done
.Lcv_p0_w_q_skip:
	s_cmp_lt_u32 s1, 656
	s_cbranch_scc0 .Lcv_p0_w_kv_skip
	s_sub_u32 s1, s1, 624
	s_lshr_b32 s3, s1, 3
	s_mul_i32 s4, s3, 8
	s_sub_u32 s4, s1, s4
	v_readlane_b32 s6, v253, 54
	v_readlane_b32 s7, v253, 55
	s_mul_i32 s5, s0, 0x200000
	s_mul_i32 s8, s3, 0x80000
	s_lshl_b32 s9, s4, 10
	s_add_u32 s5, s5, s8
	s_add_u32 s5, s5, s9
	s_add_u32 s34, s6, s5
	s_addc_u32 s35, s7, 0
	s_mov_b32 s36, 0x2000
	s_lshl_b32 s9, s4, 8
	s_mov_b32 s44, s9
	s_sub_u32 s10, 2044, s9
	s_lshl_b32 s37, s10, 2
	s_sub_u32 s45, 2047, s9
	s_add_u32 s5, s2, 0x1380000
	s_lshl_b32 s8, s3, 7
	s_add_u32 s5, s5, s8
	s_add_u32 s40, s30, s5
	s_addc_u32 s41, s31, 0
	s_mov_b32 s42, 9
	s_mov_b32 s43, 2
	v_readlane_b32 s38, v253, 6
	v_readlane_b32 s39, v253, 7
	s_mov_b32 s46, 0
	s_branch .Lcv_p0_done
.Lcv_p0_w_kv_skip:
	s_cmp_lt_u32 s1, 912
	s_cbranch_scc0 .Lcv_p0_w_out_skip
	s_sub_u32 s1, s1, 656
	s_lshr_b32 s3, s1, 3
	s_mul_i32 s4, s3, 8
	s_sub_u32 s4, s1, s4
	v_readlane_b32 s6, v253, 56
	v_readlane_b32 s7, v253, 57
	s_mul_i32 s5, s0, 0x1000000
	s_mul_i32 s8, s3, 0x80000
	s_lshl_b32 s9, s4, 10
	s_add_u32 s5, s5, s8
	s_add_u32 s5, s5, s9
	s_add_u32 s34, s6, s5
	s_addc_u32 s35, s7, 0
	s_mov_b32 s36, 0x2000
	s_lshl_b32 s9, s4, 8
	s_mov_b32 s44, s9
	s_sub_u32 s10, 2044, s9
	s_lshl_b32 s37, s10, 2
	s_sub_u32 s45, 2047, s9
	s_add_u32 s5, s2, 0x1480000
	s_lshl_b32 s8, s3, 7
	s_add_u32 s5, s5, s8
	s_add_u32 s40, s30, s5
	s_addc_u32 s41, s31, 0
	s_mov_b32 s42, 12
	s_mov_b32 s43, 0
	v_readlane_b32 s38, v253, 6
	v_readlane_b32 s39, v253, 7
	s_mov_b32 s46, 0
	s_branch .Lcv_p0_done
; __device__ __forceinline__ CvtTile cvt_get(const Params& p, int t) {
;     const int l = t / TILES_L; int r = t % TILES_L; unsigned char* Wl = p.ws + OFF_W + (size_t)l * SZ_WL; CvtTile c; int nT; c.mode = 0; c.gk = nullptr;
;     if (r < 576) { c.W = p.w_in + (size_t)l * DM * NPROJ; c.K = DM; c.N = NPROJ; nT = 18; c.dst = (bf16_t*)(Wl + WO_IN); c.gk = p.g_mix + l * DM; }
;     else if ((r -= 576) < 48) { c.W = p.w_q_up + (size_t)l * 512 * 1536; c.K = 512; c.N = 1536; nT = 6; c.mode = 1; c.dst = (bf16_t*)(Wl + WO_Q); }
;     else if ((r -= 48) < 32) { c.W = p.w_kv_up + (size_t)l * 256 * 2048; c.K = 256; c.N = 2048; nT = 8; c.mode = 2; c.dst = (bf16_t*)(Wl + WO_KV); }
;     else if ((r -= 32) < 256) { c.W = p.w_out + (size_t)l * DM * DM; c.K = DM; c.N = DM; nT = 8; c.dst = (bf16_t*)(Wl + WO_OUT); }
;     else if ((r -= 256) < 1024) { c.W = p.w_ff1 + (size_t)l * DM * DFF; c.K = DM; c.N = DFF; nT = 32; c.dst = (bf16_t*)(Wl + WO_1); c.gk = p.g_ffn + l * DM; }
;     else { r -= 1024; c.W = p.w_ff2 + (size_t)l * DFF * DM; c.K = DFF; c.N = DM; nT = 8; c.dst = (bf16_t*)(Wl + WO_2); }
;     c.kt = r / nT; c.nt = r % nT; return c;
; }
; __device__ __forceinline__ void cvt_load(const CvtTile& c, f32x4 (&v)[8], int tid) {
; #pragma unroll
;     for (int i = 0; i < 8; ++i) { const int k = (tid >> 6) + 8 * i, gn = c.nt * 256 + (tid & 63) * 4;
;         v[i] = (f32x4){0.f, 0.f, 0.f, 0.f};
;         if (gn < c.N) { v[i] = __builtin_nontemporal_load((const f32x4*)(c.W + (size_t)(c.kt * 64 + k) * c.N + gn)); if (c.gk) v[i] = v[i] * c.gk[c.kt * 64 + k]; } }
; }
.Lcv_p0_w_out_skip:
	s_cmp_lt_u32 s1, 1936
	s_cbranch_scc0 .Lcv_p0_w_1_skip
	s_sub_u32 s1, s1, 912
	s_lshr_b32 s3, s1, 5
	s_mul_i32 s4, s3, 32
	s_sub_u32 s4, s1, s4
	v_readlane_b32 s6, v253, 60
	v_readlane_b32 s7, v253, 61
	s_mul_i32 s5, s0, 0x4000000
	s_mul_i32 s8, s3, 0x200000
	s_lshl_b32 s9, s4, 10
	s_add_u32 s5, s5, s8
	s_add_u32 s5, s5, s9
	s_add_u32 s34, s6, s5
	s_addc_u32 s35, s7, 0
	s_mov_b32 s36, 0x8000
	s_lshl_b32 s9, s4, 8
	s_mov_b32 s44, s9
	s_sub_u32 s10, 8188, s9
	s_lshl_b32 s37, s10, 2
	s_sub_u32 s45, 8191, s9
	s_add_u32 s5, s2, 0x1c80000
	s_lshl_b32 s8, s3, 7
	s_add_u32 s5, s5, s8
	s_add_u32 s40, s30, s5
	s_addc_u32 s41, s31, 0
	s_mov_b32 s42, 12
	s_mov_b32 s43, 0
	v_readlane_b32 s6, v253, 58
	v_readlane_b32 s7, v253, 59
	s_lshl_b32 s5, s0, 13
	s_lshl_b32 s8, s3, 8
	s_add_u32 s5, s5, s8
	s_add_u32 s38, s6, s5
	s_addc_u32 s39, s7, 0
	s_mov_b32 s46, 1
	s_branch .Lcv_p0_done
.Lcv_p0_w_1_skip:
	s_sub_u32 s1, s1, 1936
	s_lshr_b32 s3, s1, 3
	s_mul_i32 s4, s3, 8
	s_sub_u32 s4, s1, s4
	v_readlane_b32 s6, v253, 62
	v_readlane_b32 s7, v253, 63
	s_mul_i32 s5, s0, 0x4000000
	s_mul_i32 s8, s3, 0x80000
	s_lshl_b32 s9, s4, 10
	s_add_u32 s5, s5, s8
	s_add_u32 s5, s5, s9
	s_add_u32 s34, s6, s5
	s_addc_u32 s35, s7, 0
	s_mov_b32 s36, 0x2000
	s_lshl_b32 s9, s4, 8
	s_mov_b32 s44, s9
	s_sub_u32 s10, 2044, s9
	s_lshl_b32 s37, s10, 2
	s_sub_u32 s45, 2047, s9
	s_add_u32 s5, s2, 0x3c80000
	s_lshl_b32 s8, s3, 7
	s_add_u32 s5, s5, s8
	s_add_u32 s40, s30, s5
	s_addc_u32 s41, s31, 0
	s_mov_b32 s42, 14
	s_mov_b32 s43, 0
	v_readlane_b32 s38, v253, 6
	v_readlane_b32 s39, v253, 7
	s_mov_b32 s46, 0
.Lcv_p0_done:
	s_mul_i32 s0, s28, s36
	s_lshl_b32 s0, s0, 3
	v_min_u32_e32 v166, s37, v160
	v_add_u32_e32 v166, s0, v166
	global_load_dwordx4 v[0:3], v166, s[34:35] nt
	v_add_u32_e32 v166, s36, v166
	global_load_dwordx4 v[4:7], v166, s[34:35] nt
	v_add_u32_e32 v166, s36, v166
	global_load_dwordx4 v[8:11], v166, s[34:35] nt
	v_add_u32_e32 v166, s36, v166
	global_load_dwordx4 v[12:15], v166, s[34:35] nt
	v_add_u32_e32 v166, s36, v166
	global_load_dwordx4 v[16:19], v166, s[34:35] nt
	v_add_u32_e32 v166, s36, v166
	global_load_dwordx4 v[20:23], v166, s[34:35] nt
	v_add_u32_e32 v166, s36, v166
	global_load_dwordx4 v[24:27], v166, s[34:35] nt
	v_add_u32_e32 v166, s36, v166
	global_load_dwordx4 v[28:31], v166, s[34:35] nt
	global_load_dwordx4 v[96:99], v164, s[38:39]
	global_load_dwordx4 v[100:103], v164, s[38:39] offset:16
	s_mov_b32 s64, s40
	s_mov_b32 s65, s41
	s_mov_b32 s66, s42
	s_mov_b32 s67, s43
	s_mov_b32 s68, s44
	s_mov_b32 s69, s45
	s_mov_b32 s70, s46
	s_add_u32 s26, s26, s25
	s_mov_b32 s0, 0
	s_cmp_ge_u32 s26, 2960
	s_addc_u32 s0, s0, 0
	s_cmp_ge_u32 s26, 5920
	s_addc_u32 s0, s0, 0
	s_cmp_ge_u32 s26, 8880
	s_addc_u32 s0, s0, 0
	s_mul_i32 s1, s0, 2960
	s_sub_u32 s1, s26, s1
	s_mul_i32 s2, s0, 0x5c80000
	s_cmp_lt_u32 s1, 576
	s_cbranch_scc0 .Lcv_p1_w_in_skip
	s_mul_i32 s3, s1, 3641
	s_lshr_b32 s3, s3, 16
	s_mul_i32 s4, s3, 18
	s_sub_u32 s4, s1, s4
	v_readlane_b32 s6, v253, 8
	v_readlane_b32 s7, v253, 9
	s_mul_i32 s5, s0, 0x22a0000
	s_mul_i32 s8, s3, 0x115000
	s_lshl_b32 s9, s4, 10
	s_add_u32 s5, s5, s8
	s_add_u32 s5, s5, s9
	s_add_u32 s34, s6, s5
	s_addc_u32 s35, s7, 0
	s_mov_b32 s36, 0x4540
	s_lshl_b32 s9, s4, 8
	s_mov_b32 s44, s9
	s_sub_u32 s10, 4428, s9
	s_lshl_b32 s37, s10, 2
	s_sub_u32 s45, 4431, s9
	s_add_u32 s5, s2, 0x0
	s_lshl_b32 s8, s3, 7
	s_add_u32 s5, s5, s8
	s_add_u32 s40, s30, s5
	s_addc_u32 s41, s31, 0
	s_mov_b32 s42, 12
	s_mov_b32 s43, 0
	v_readlane_b32 s6, v253, 6
	v_readlane_b32 s7, v253, 7
	s_lshl_b32 s5, s0, 13
	s_lshl_b32 s8, s3, 8
	s_add_u32 s5, s5, s8
	s_add_u32 s38, s6, s5
	s_addc_u32 s39, s7, 0
	s_mov_b32 s46, 1
	s_branch .Lcv_p1_done

; __device__ __forceinline__ CvtTile cvt_get(const Params& p, int t) {
;     const int l = t / TILES_L; int r = t % TILES_L; unsigned char* Wl = p.ws + OFF_W + (size_t)l * SZ_WL; CvtTile c; int nT; c.mode = 0; c.gk = nullptr;
;     if (r < 576) { c.W = p.w_in + (size_t)l * DM * NPROJ; c.K = DM; c.N = NPROJ; nT = 18; c.dst = (bf16_t*)(Wl + WO_IN); c.gk = p.g_mix + l * DM; }
;     else if ((r -= 576) < 48) { c.W = p.w_q_up + (size_t)l * 512 * 1536; c.K = 512; c.N = 1536; nT = 6; c.mode = 1; c.dst = (bf16_t*)(Wl + WO_Q); }
;     else if ((r -= 48) < 32) { c.W = p.w_kv_up + (size_t)l * 256 * 2048; c.K = 256; c.N = 2048; nT = 8; c.mode = 2; c.dst = (bf16_t*)(Wl + WO_KV); }
;     else if ((r -= 32) < 256) { c.W = p.w_out + (size_t)l * DM * DM; c.K = DM; c.N = DM; nT = 8; c.dst = (bf16_t*)(Wl + WO_OUT); }
;     else if ((r -= 256) < 1024) { c.W = p.w_ff1 + (size_t)l * DM * DFF; c.K = DM; c.N = DFF; nT = 32; c.dst = (bf16_t*)(Wl + WO_1); c.gk = p.g_ffn + l * DM; }
;     else { r -= 1024; c.W = p.w_ff2 + (size_t)l * DFF * DM; c.K = DFF; c.N = DM; nT = 8; c.dst = (bf16_t*)(Wl + WO_2); }
;     c.kt = r / nT; c.nt = r % nT; return c;
; }
; __device__ __forceinline__ void cvt_load(const CvtTile& c, f32x4 (&v)[8], int tid) {
; #pragma unroll
;     for (int i = 0; i < 8; ++i) { const int k = (tid >> 6) + 8 * i, gn = c.nt * 256 + (tid & 63) * 4;
;         v[i] = (f32x4){0.f, 0.f, 0.f, 0.f};
;         if (gn < c.N) { v[i] = __builtin_nontemporal_load((const f32x4*)(c.W + (size_t)(c.kt * 64 + k) * c.N + gn)); if (c.gk) v[i] = v[i] * c.gk[c.kt * 64 + k]; } }
; }
.Lcv_p1_done:
	s_mul_i32 s0, s28, s36
	s_lshl_b32 s0, s0, 3
	v_min_u32_e32 v166, s37, v160
	v_add_u32_e32 v166, s0, v166
	global_load_dwordx4 v[32:35], v166, s[34:35] nt
	v_add_u32_e32 v166, s36, v166
	global_load_dwordx4 v[36:39], v166, s[34:35] nt
	v_add_u32_e32 v166, s36, v166
	global_load_dwordx4 v[40:43], v166, s[34:35] nt
	v_add_u32_e32 v166, s36, v166
	global_load_dwordx4 v[44:47], v166, s[34:35] nt
	v_add_u32_e32 v166, s36, v166
	global_load_dwordx4 v[48:51], v166, s[34:35] nt
	v_add_u32_e32 v166, s36, v166
	global_load_dwordx4 v[52:55], v166, s[34:35] nt
	v_add_u32_e32 v166, s36, v166
	global_load_dwordx4 v[56:59], v166, s[34:35] nt
	v_add_u32_e32 v166, s36, v166
	global_load_dwordx4 v[60:63], v166, s[34:35] nt
	global_load_dwordx4 v[104:107], v164, s[38:39]
	global_load_dwordx4 v[108:111], v164, s[38:39] offset:16
	s_mov_b32 s72, s40
	s_mov_b32 s73, s41
	s_mov_b32 s74, s42
	s_mov_b32 s75, s43
	s_mov_b32 s76, s44
	s_mov_b32 s77, s45
	s_mov_b32 s78, s46
	s_add_u32 s26, s26, s25
	s_mov_b32 s0, 0
	s_cmp_ge_u32 s26, 2960
	s_addc_u32 s0, s0, 0
	s_cmp_ge_u32 s26, 5920
	s_addc_u32 s0, s0, 0
	s_cmp_ge_u32 s26, 8880
	s_addc_u32 s0, s0, 0
	s_mul_i32 s1, s0, 2960
	s_sub_u32 s1, s26, s1
	s_mul_i32 s2, s0, 0x5c80000
	s_cmp_lt_u32 s1, 576
	s_cbranch_scc0 .Lcv_p2_w_in_skip
	s_mul_i32 s3, s1, 3641
	s_lshr_b32 s3, s3, 16
	s_mul_i32 s4, s3, 18
	s_sub_u32 s4, s1, s4
	v_readlane_b32 s6, v253, 8
	v_readlane_b32 s7, v253, 9
	s_mul_i32 s5, s0, 0x22a0000
	s_mul_i32 s8, s3, 0x115000
	s_lshl_b32 s9, s4, 10
	s_add_u32 s5, s5, s8
	s_add_u32 s5, s5, s9
	s_add_u32 s34, s6, s5
	s_addc_u32 s35, s7, 0
	s_mov_b32 s36, 0x4540
	s_lshl_b32 s9, s4, 8
	s_mov_b32 s44, s9
	s_sub_u32 s10, 4428, s9
	s_lshl_b32 s37, s10, 2
	s_sub_u32 s45, 4431, s9
	s_add_u32 s5, s2, 0x0
	s_lshl_b32 s8, s3, 7
	s_add_u32 s5, s5, s8
	s_add_u32 s40, s30, s5
	s_addc_u32 s41, s31, 0
	s_mov_b32 s42, 12
	s_mov_b32 s43, 0
	v_readlane_b32 s6, v253, 6
	v_readlane_b32 s7, v253, 7
	s_lshl_b32 s5, s0, 13
	s_lshl_b32 s8, s3, 8
	s_add_u32 s5, s5, s8
	s_add_u32 s38, s6, s5
	s_addc_u32 s39, s7, 0
	s_mov_b32 s46, 1
	s_branch .Lcv_p2_done

; #define LAS __attribute__((address_space(3)))
; __device__ __forceinline__ int ltid() { int t = threadIdx.x; asm volatile("" : "+v"(t)); return t; }
; __device__ __forceinline__ int lbid() { int t = blockIdx.x; asm volatile("" : "+s"(t)); return t; }
; __device__ __forceinline__ void cvt_load(const CvtTile& c, f32x4 (&v)[8], int tid) {
; #pragma unroll
;     for (int i = 0; i < 8; ++i) { const int k = (tid >> 6) + 8 * i, gn = c.nt * 256 + (tid & 63) * 4;
;         v[i] = (f32x4){0.f, 0.f, 0.f, 0.f};
;         if (gn < c.N) { v[i] = __builtin_nontemporal_load((const f32x4*)(c.W + (size_t)(c.kt * 64 + k) * c.N + gn)); if (c.gk) v[i] = v[i] * c.gk[c.kt * 64 + k]; } }
; }
; __device__ __forceinline__ void convert_phase(const Params& p, LAS unsigned char* lds) {
;     LAS float* T = (LAS float*)lds;
;     const int tid = ltid(), G = gridDim.x;
;     int t = lbid();
;     f32x4 v[8]; CvtTile c;
;     if (t < NLAYER * TILES_L) { c = cvt_get(p, t); cvt_load(c, v, tid); }
;     while (t < NLAYER * TILES_L) {
; #pragma unroll
;         for (int i = 0; i < 8; ++i) { const int k = (tid >> 6) + 8 * i, n4 = (tid & 63) * 4;
;             T[k * 257 + n4] = v[i][0]; T[k * 257 + n4 + 1] = v[i][1]; T[k * 257 + n4 + 2] = v[i][2]; T[k * 257 + n4 + 3] = v[i][3]; }
;         __syncthreads();
;         const CvtTile cur = c; const int tn = t + G;
;         if (tn < NLAYER * TILES_L) { c = cvt_get(p, tn); cvt_load(c, v, tid); }
.Lcv_p2_done:
	s_mul_i32 s0, s28, s36
	s_lshl_b32 s0, s0, 3
	v_min_u32_e32 v166, s37, v160
	v_add_u32_e32 v166, s0, v166
	global_load_dwordx4 v[64:67], v166, s[34:35] nt
	v_add_u32_e32 v166, s36, v166
	global_load_dwordx4 v[68:71], v166, s[34:35] nt
	v_add_u32_e32 v166, s36, v166
	global_load_dwordx4 v[72:75], v166, s[34:35] nt
	v_add_u32_e32 v166, s36, v166
	global_load_dwordx4 v[76:79], v166, s[34:35] nt
	v_add_u32_e32 v166, s36, v166
	global_load_dwordx4 v[80:83], v166, s[34:35] nt
	v_add_u32_e32 v166, s36, v166
	global_load_dwordx4 v[84:87], v166, s[34:35] nt
	v_add_u32_e32 v166, s36, v166
	global_load_dwordx4 v[88:91], v166, s[34:35] nt
	v_add_u32_e32 v166, s36, v166
	global_load_dwordx4 v[92:95], v166, s[34:35] nt
	global_load_dwordx4 v[112:115], v164, s[38:39]
	global_load_dwordx4 v[116:119], v164, s[38:39] offset:16
	s_mov_b32 s48, s40
	s_mov_b32 s49, s41
	s_mov_b32 s50, s42
	s_mov_b32 s51, s43
	s_mov_b32 s52, s44
	s_mov_b32 s47, s45
	s_mov_b32 s33, s46
	s_add_u32 s26, s26, s25
.Lcv_loop:
	s_cmp_eq_u32 s29, 0
	s_cbranch_scc0 .Lcv_w0_0
	s_waitcnt vmcnt(20)
	s_branch .Lcv_w1_0

; __device__ __forceinline__ void convert_phase(const Params& p, LAS unsigned char* lds) {
;     ...
;     while (t < NLAYER * TILES_L) {
; #pragma unroll
;         for (int i = 0; i < 8; ++i) { const int k = (tid >> 6) + 8 * i, n4 = (tid & 63) * 4;
;             T[k * 257 + n4] = v[i][0]; T[k * 257 + n4 + 1] = v[i][1]; T[k * 257 + n4 + 2] = v[i][2]; T[k * 257 + n4 + 3] = v[i][3]; }
;         __syncthreads();
;         const CvtTile cur = c; const int tn = t + G;
;         if (tn < NLAYER * TILES_L) { c = cvt_get(p, tn); cvt_load(c, v, tid); }
.Lcv_w1_0:
	v_add_u32_e32 v171, s27, v161
	ds_write_b32 v171, v0 offset:0
	ds_write_b32 v171, v1 offset:4
	ds_write_b32 v171, v2 offset:8
	ds_write_b32 v171, v3 offset:12
	ds_write_b32 v171, v4 offset:1028
	ds_write_b32 v171, v5 offset:1032
	ds_write_b32 v171, v6 offset:1036
	ds_write_b32 v171, v7 offset:1040
	ds_write_b32 v171, v8 offset:2056
	ds_write_b32 v171, v9 offset:2060
	ds_write_b32 v171, v10 offset:2064
	ds_write_b32 v171, v11 offset:2068
	ds_write_b32 v171, v12 offset:3084
	ds_write_b32 v171, v13 offset:3088
	ds_write_b32 v171, v14 offset:3092
	ds_write_b32 v171, v15 offset:3096
	ds_write_b32 v171, v16 offset:4112
	ds_write_b32 v171, v17 offset:4116
	ds_write_b32 v171, v18 offset:4120
	ds_write_b32 v171, v19 offset:4124
	ds_write_b32 v171, v20 offset:5140
	ds_write_b32 v171, v21 offset:5144
	ds_write_b32 v171, v22 offset:5148
	ds_write_b32 v171, v23 offset:5152
	ds_write_b32 v171, v24 offset:6168
	ds_write_b32 v171, v25 offset:6172
	ds_write_b32 v171, v26 offset:6176
	ds_write_b32 v171, v27 offset:6180
	ds_write_b32 v171, v28 offset:7196
	ds_write_b32 v171, v29 offset:7200
	ds_write_b32 v171, v30 offset:7204
	ds_write_b32 v171, v31 offset:7208
	s_cmp_lt_u32 s26, 11840
	s_cbranch_scc0 .Lcv_nold_0
	s_mov_b32 s0, 0
	s_cmp_ge_u32 s26, 2960
	s_addc_u32 s0, s0, 0
	s_cmp_ge_u32 s26, 5920
	s_addc_u32 s0, s0, 0
	s_cmp_ge_u32 s26, 8880
	s_addc_u32 s0, s0, 0
	s_mul_i32 s1, s0, 2960
	s_sub_u32 s1, s26, s1
	s_mul_i32 s2, s0, 0x5c80000
	s_cmp_lt_u32 s1, 576
	s_cbranch_scc0 .Lcv_d0_w_in_skip
	s_mul_i32 s3, s1, 3641
	s_lshr_b32 s3, s3, 16
	s_mul_i32 s4, s3, 18
	s_sub_u32 s4, s1, s4
	v_readlane_b32 s6, v253, 8
	v_readlane_b32 s7, v253, 9
	s_mul_i32 s5, s0, 0x22a0000
	s_mul_i32 s8, s3, 0x115000
	s_lshl_b32 s9, s4, 10
	s_add_u32 s5, s5, s8
	s_add_u32 s5, s5, s9
	s_add_u32 s34, s6, s5
	s_addc_u32 s35, s7, 0
	s_mov_b32 s36, 0x4540
	s_lshl_b32 s9, s4, 8
	s_mov_b32 s44, s9
	s_sub_u32 s10, 4428, s9
	s_lshl_b32 s37, s10, 2
	s_sub_u32 s45, 4431, s9
	s_add_u32 s5, s2, 0x0
	s_lshl_b32 s8, s3, 7
	s_add_u32 s5, s5, s8
	s_add_u32 s40, s30, s5
	s_addc_u32 s41, s31, 0
	s_mov_b32 s42, 12
	s_mov_b32 s43, 0
	v_readlane_b32 s6, v253, 6
	v_readlane_b32 s7, v253, 7
	s_lshl_b32 s5, s0, 13
	s_lshl_b32 s8, s3, 8
	s_add_u32 s5, s5, s8
	s_add_u32 s38, s6, s5
	s_addc_u32 s39, s7, 0
	s_mov_b32 s46, 1
	s_branch .Lcv_d0_done

; __device__ __forceinline__ u32x4 pack8(const float* f) { u32x4 w; w.x = cvt_pk_bf16(f[0], f[1]); w.y = cvt_pk_bf16(f[2], f[3]); w.z = cvt_pk_bf16(f[4], f[5]); w.w = cvt_pk_bf16(f[6], f[7]); return w; }
; __device__ __forceinline__ void convert_phase(const Params& p, LAS unsigned char* lds) {
;     ...
;     while (t < NLAYER * TILES_L) {
; #pragma unroll
;         for (int i = 0; i < 8; ++i) { const int k = (tid >> 6) + 8 * i, n4 = (tid & 63) * 4;
;             T[k * 257 + n4] = v[i][0]; T[k * 257 + n4 + 1] = v[i][1]; T[k * 257 + n4 + 2] = v[i][2]; T[k * 257 + n4 + 3] = v[i][3]; }
;         __syncthreads();
;         const CvtTile cur = c; const int tn = t + G;
;         if (tn < NLAYER * TILES_L) { c = cvt_get(p, tn); cvt_load(c, v, tid); }
; #pragma unroll
;         for (int i = 0; i < 4; ++i) { const int ch = tid + 512 * i, n = ch >> 3, k8 = (ch & 7) * 8, gn = cur.nt * 256 + n;
;             if (gn < cur.N) { float f[8];
; #pragma unroll
;                 for (int j = 0; j < 8; ++j) f[j] = T[(k8 + j) * 257 + n];
;                 *(u32x4*)(cur.dst + (size_t)map_col(gn, cur.mode) * cur.K + cur.kt * 64 + k8) = pack8(f); } }
;         __syncthreads();
;         t = tn;
.Lcv_d0_done:
	s_mul_i32 s0, s28, s36
	s_lshl_b32 s0, s0, 3
	v_min_u32_e32 v166, s37, v160
	v_add_u32_e32 v166, s0, v166
	global_load_dwordx4 v[0:3], v166, s[34:35] nt
	v_add_u32_e32 v166, s36, v166
	global_load_dwordx4 v[4:7], v166, s[34:35] nt
	v_add_u32_e32 v166, s36, v166
	global_load_dwordx4 v[8:11], v166, s[34:35] nt
	v_add_u32_e32 v166, s36, v166
	global_load_dwordx4 v[12:15], v166, s[34:35] nt
	v_add_u32_e32 v166, s36, v166
	global_load_dwordx4 v[16:19], v166, s[34:35] nt
	v_add_u32_e32 v166, s36, v166
	global_load_dwordx4 v[20:23], v166, s[34:35] nt
	v_add_u32_e32 v166, s36, v166
	global_load_dwordx4 v[24:27], v166, s[34:35] nt
	v_add_u32_e32 v166, s36, v166
	global_load_dwordx4 v[28:31], v166, s[34:35] nt
	s_branch .Lcv_ld_0
.Lcv_nold_0:
	s_mov_b32 s29, 1
.Lcv_ld_0:
	s_waitcnt lgkmcnt(0)
	s_barrier
	v_add_u32_e32 v172, s27, v162
	v_mov_b32_e32 v181, v165
	v_min_u32_e32 v181, s69, v181
	v_lshl_add_u32 v173, v181, 2, v172
	v_add_u32_e32 v182, 64, v165
	v_min_u32_e32 v182, s69, v182
	v_lshl_add_u32 v174, v182, 2, v172
	v_add_u32_e32 v183, 128, v165
	v_min_u32_e32 v183, s69, v183
	v_lshl_add_u32 v175, v183, 2, v172
	v_add_u32_e32 v184, 192, v165
	v_min_u32_e32 v184, s69, v184
	v_lshl_add_u32 v176, v184, 2, v172
	ds_read_b32 v120, v173 offset:0
	ds_read_b32 v121, v173 offset:1028
	ds_read_b32 v122, v173 offset:2056
	ds_read_b32 v123, v173 offset:3084
	ds_read_b32 v124, v173 offset:4112
	ds_read_b32 v125, v173 offset:5140
	ds_read_b32 v126, v173 offset:6168
	ds_read_b32 v127, v173 offset:7196
	ds_read_b32 v128, v174 offset:0
	ds_read_b32 v129, v174 offset:1028
	ds_read_b32 v130, v174 offset:2056
	ds_read_b32 v131, v174 offset:3084
	ds_read_b32 v132, v174 offset:4112
	ds_read_b32 v133, v174 offset:5140
	ds_read_b32 v134, v174 offset:6168
	ds_read_b32 v135, v174 offset:7196
	ds_read_b32 v136, v175 offset:0
	ds_read_b32 v137, v175 offset:1028
	ds_read_b32 v138, v175 offset:2056
	ds_read_b32 v139, v175 offset:3084
	ds_read_b32 v140, v175 offset:4112
	ds_read_b32 v141, v175 offset:5140
	ds_read_b32 v142, v175 offset:6168
	ds_read_b32 v143, v175 offset:7196
	ds_read_b32 v144, v176 offset:0
	ds_read_b32 v145, v176 offset:1028
	ds_read_b32 v146, v176 offset:2056
	ds_read_b32 v147, v176 offset:3084
	ds_read_b32 v148, v176 offset:4112
	ds_read_b32 v149, v176 offset:5140
	ds_read_b32 v150, v176 offset:6168
	ds_read_b32 v151, v176 offset:7196
	s_cmp_eq_u32 s67, 0
	s_cbranch_scc0 .Lcv_perm_0
	v_add_u32_e32 v177, s68, v181
	v_add_u32_e32 v178, s68, v182
	v_add_u32_e32 v179, s68, v183
	v_add_u32_e32 v180, s68, v184
.Lcv_permback_0:
	v_lshlrev_b32_e32 v177, s66, v177
	v_add_u32_e32 v177, v177, v163
	v_lshlrev_b32_e32 v178, s66, v178
	v_add_u32_e32 v178, v178, v163
	v_lshlrev_b32_e32 v179, s66, v179
	v_add_u32_e32 v179, v179, v163
	v_lshlrev_b32_e32 v180, s66, v180
	v_add_u32_e32 v180, v180, v163
	s_cmp_eq_u32 s70, 0
	s_cbranch_scc1 .Lcv_nogk_0
	s_waitcnt lgkmcnt(0)
	v_mul_f32_e32 v120, v120, v96
	v_mul_f32_e32 v121, v121, v97
	v_mul_f32_e32 v122, v122, v98
	v_mul_f32_e32 v123, v123, v99
	v_mul_f32_e32 v124, v124, v100
	v_mul_f32_e32 v125, v125, v101
	v_mul_f32_e32 v126, v126, v102
	v_mul_f32_e32 v127, v127, v103
	v_mul_f32_e32 v128, v128, v96
	v_mul_f32_e32 v129, v129, v97
	v_mul_f32_e32 v130, v130, v98
	v_mul_f32_e32 v131, v131, v99
	v_mul_f32_e32 v132, v132, v100
	v_mul_f32_e32 v133, v133, v101
	v_mul_f32_e32 v134, v134, v102
	v_mul_f32_e32 v135, v135, v103
	v_mul_f32_e32 v136, v136, v96
	v_mul_f32_e32 v137, v137, v97
	v_mul_f32_e32 v138, v138, v98
	v_mul_f32_e32 v139, v139, v99
	v_mul_f32_e32 v140, v140, v100
	v_mul_f32_e32 v141, v141, v101
	v_mul_f32_e32 v142, v142, v102
	v_mul_f32_e32 v143, v143, v103
	v_mul_f32_e32 v144, v144, v96
	v_mul_f32_e32 v145, v145, v97
	v_mul_f32_e32 v146, v146, v98
	v_mul_f32_e32 v147, v147, v99
	v_mul_f32_e32 v148, v148, v100
	v_mul_f32_e32 v149, v149, v101
	v_mul_f32_e32 v150, v150, v102
	v_mul_f32_e32 v151, v151, v103
.Lcv_nogk_0:
	s_waitcnt lgkmcnt(0)
	v_cvt_pk_bf16_f32 v152, v120, v121
	v_cvt_pk_bf16_f32 v153, v122, v123
	v_cvt_pk_bf16_f32 v154, v124, v125
	v_cvt_pk_bf16_f32 v155, v126, v127
	global_store_dwordx4 v177, v[152:155], s[64:65]
	s_nop 1
	v_cvt_pk_bf16_f32 v152, v128, v129
	v_cvt_pk_bf16_f32 v153, v130, v131
	v_cvt_pk_bf16_f32 v154, v132, v133
	v_cvt_pk_bf16_f32 v155, v134, v135
	global_store_dwordx4 v178, v[152:155], s[64:65]
	s_nop 1
	v_cvt_pk_bf16_f32 v152, v136, v137
	v_cvt_pk_bf16_f32 v153, v138, v139
	v_cvt_pk_bf16_f32 v154, v140, v141
	v_cvt_pk_bf16_f32 v155, v142, v143
	global_store_dwordx4 v179, v[152:155], s[64:65]
	s_nop 1
	v_cvt_pk_bf16_f32 v152, v144, v145
	v_cvt_pk_bf16_f32 v153, v146, v147
	v_cvt_pk_bf16_f32 v154, v148, v149
	v_cvt_pk_bf16_f32 v155, v150, v151
	global_store_dwordx4 v180, v[152:155], s[64:65]
	s_cmp_eq_u32 s29, 0
	s_cbranch_scc0 .Lcv_nog_0
	global_load_dwordx4 v[96:99], v164, s[38:39]
	global_load_dwordx4 v[100:103], v164, s[38:39] offset:16
	s_mov_b32 s64, s40
	s_mov_b32 s65, s41
	s_mov_b32 s66, s42
	s_mov_b32 s67, s43
	s_mov_b32 s68, s44
	s_mov_b32 s69, s45
	s_mov_b32 s70, s46
.Lcv_nog_0:
	s_add_u32 s26, s26, s25
	s_xor_b32 s27, s27, 65792
	s_mul_i32 s0, s25, 3
	s_sub_u32 s0, s26, s0
	s_cmp_lt_u32 s0, 11840
	s_cbranch_scc0 .Lcv_exit
	s_cmp_eq_u32 s29, 0
	s_cbranch_scc0 .Lcv_w0_1
	s_waitcnt vmcnt(20)
	s_branch .Lcv_w1_1

; __device__ __forceinline__ void convert_phase(const Params& p, LAS unsigned char* lds) {
;     ...
;     while (t < NLAYER * TILES_L) {
; #pragma unroll
;         for (int i = 0; i < 8; ++i) { const int k = (tid >> 6) + 8 * i, n4 = (tid & 63) * 4;
;             T[k * 257 + n4] = v[i][0]; T[k * 257 + n4 + 1] = v[i][1]; T[k * 257 + n4 + 2] = v[i][2]; T[k * 257 + n4 + 3] = v[i][3]; }
;         __syncthreads();
;         const CvtTile cur = c; const int tn = t + G;
;         if (tn < NLAYER * TILES_L) { c = cvt_get(p, tn); cvt_load(c, v, tid); }
.Lcv_w1_1:
	v_add_u32_e32 v171, s27, v161
	ds_write_b32 v171, v32 offset:0
	ds_write_b32 v171, v33 offset:4
	ds_write_b32 v171, v34 offset:8
	ds_write_b32 v171, v35 offset:12
	ds_write_b32 v171, v36 offset:1028
	ds_write_b32 v171, v37 offset:1032
	ds_write_b32 v171, v38 offset:1036
	ds_write_b32 v171, v39 offset:1040
	ds_write_b32 v171, v40 offset:2056
	ds_write_b32 v171, v41 offset:2060
	ds_write_b32 v171, v42 offset:2064
	ds_write_b32 v171, v43 offset:2068
	ds_write_b32 v171, v44 offset:3084
	ds_write_b32 v171, v45 offset:3088
	ds_write_b32 v171, v46 offset:3092
	ds_write_b32 v171, v47 offset:3096
	ds_write_b32 v171, v48 offset:4112
	ds_write_b32 v171, v49 offset:4116
	ds_write_b32 v171, v50 offset:4120
	ds_write_b32 v171, v51 offset:4124
	ds_write_b32 v171, v52 offset:5140
	ds_write_b32 v171, v53 offset:5144
	ds_write_b32 v171, v54 offset:5148
	ds_write_b32 v171, v55 offset:5152
	ds_write_b32 v171, v56 offset:6168
	ds_write_b32 v171, v57 offset:6172
	ds_write_b32 v171, v58 offset:6176
	ds_write_b32 v171, v59 offset:6180
	ds_write_b32 v171, v60 offset:7196
	ds_write_b32 v171, v61 offset:7200
	ds_write_b32 v171, v62 offset:7204
	ds_write_b32 v171, v63 offset:7208
	s_cmp_lt_u32 s26, 11840
	s_cbranch_scc0 .Lcv_nold_1
	s_mov_b32 s0, 0
	s_cmp_ge_u32 s26, 2960
	s_addc_u32 s0, s0, 0
	s_cmp_ge_u32 s26, 5920
	s_addc_u32 s0, s0, 0
	s_cmp_ge_u32 s26, 8880
	s_addc_u32 s0, s0, 0
	s_mul_i32 s1, s0, 2960
	s_sub_u32 s1, s26, s1
	s_mul_i32 s2, s0, 0x5c80000
	s_cmp_lt_u32 s1, 576
	s_cbranch_scc0 .Lcv_d1_w_in_skip
	s_mul_i32 s3, s1, 3641
	s_lshr_b32 s3, s3, 16
	s_mul_i32 s4, s3, 18
	s_sub_u32 s4, s1, s4
	v_readlane_b32 s6, v253, 8
	v_readlane_b32 s7, v253, 9
	s_mul_i32 s5, s0, 0x22a0000
	s_mul_i32 s8, s3, 0x115000
	s_lshl_b32 s9, s4, 10
	s_add_u32 s5, s5, s8
	s_add_u32 s5, s5, s9
	s_add_u32 s34, s6, s5
	s_addc_u32 s35, s7, 0
	s_mov_b32 s36, 0x4540
	s_lshl_b32 s9, s4, 8
	s_mov_b32 s44, s9
	s_sub_u32 s10, 4428, s9
	s_lshl_b32 s37, s10, 2
	s_sub_u32 s45, 4431, s9
	s_add_u32 s5, s2, 0x0
	s_lshl_b32 s8, s3, 7
	s_add_u32 s5, s5, s8
	s_add_u32 s40, s30, s5
	s_addc_u32 s41, s31, 0
	s_mov_b32 s42, 12
	s_mov_b32 s43, 0
	v_readlane_b32 s6, v253, 6
	v_readlane_b32 s7, v253, 7
	s_lshl_b32 s5, s0, 13
	s_lshl_b32 s8, s3, 8
	s_add_u32 s5, s5, s8
	s_add_u32 s38, s6, s5
	s_addc_u32 s39, s7, 0
	s_mov_b32 s46, 1
	s_branch .Lcv_d1_done

; __device__ __forceinline__ void cvt_load(const CvtTile& c, f32x4 (&v)[8], int tid) {
; #pragma unroll
;     for (int i = 0; i < 8; ++i) { const int k = (tid >> 6) + 8 * i, gn = c.nt * 256 + (tid & 63) * 4;
;         v[i] = (f32x4){0.f, 0.f, 0.f, 0.f};
;         if (gn < c.N) { v[i] = __builtin_nontemporal_load((const f32x4*)(c.W + (size_t)(c.kt * 64 + k) * c.N + gn)); if (c.gk) v[i] = v[i] * c.gk[c.kt * 64 + k]; } }
; }
.Lcv_d1_done:
	s_mul_i32 s0, s28, s36
	s_lshl_b32 s0, s0, 3
	v_min_u32_e32 v166, s37, v160
	v_add_u32_e32 v166, s0, v166
	global_load_dwordx4 v[32:35], v166, s[34:35] nt
	v_add_u32_e32 v166, s36, v166
	global_load_dwordx4 v[36:39], v166, s[34:35] nt
	v_add_u32_e32 v166, s36, v166
	global_load_dwordx4 v[40:43], v166, s[34:35] nt
	v_add_u32_e32 v166, s36, v166
	global_load_dwordx4 v[44:47], v166, s[34:35] nt
	v_add_u32_e32 v166, s36, v166
	global_load_dwordx4 v[48:51], v166, s[34:35] nt
	v_add_u32_e32 v166, s36, v166
	global_load_dwordx4 v[52:55], v166, s[34:35] nt
	v_add_u32_e32 v166, s36, v166
	global_load_dwordx4 v[56:59], v166, s[34:35] nt
	v_add_u32_e32 v166, s36, v166
	global_load_dwordx4 v[60:63], v166, s[34:35] nt
	s_branch .Lcv_ld_1

; __device__ __forceinline__ u32x4 pack8(const float* f) { u32x4 w; w.x = cvt_pk_bf16(f[0], f[1]); w.y = cvt_pk_bf16(f[2], f[3]); w.z = cvt_pk_bf16(f[4], f[5]); w.w = cvt_pk_bf16(f[6], f[7]); return w; }
; __device__ __forceinline__ void convert_phase(const Params& p, LAS unsigned char* lds) {
;     ...
;             T[k * 257 + n4] = v[i][0]; T[k * 257 + n4 + 1] = v[i][1]; T[k * 257 + n4 + 2] = v[i][2]; T[k * 257 + n4 + 3] = v[i][3]; }
;         __syncthreads();
;         const CvtTile cur = c; const int tn = t + G;
;         if (tn < NLAYER * TILES_L) { c = cvt_get(p, tn); cvt_load(c, v, tid); }
; #pragma unroll
;         for (int i = 0; i < 4; ++i) { const int ch = tid + 512 * i, n = ch >> 3, k8 = (ch & 7) * 8, gn = cur.nt * 256 + n;
;             if (gn < cur.N) { float f[8];
; #pragma unroll
;                 for (int j = 0; j < 8; ++j) f[j] = T[(k8 + j) * 257 + n];
;                 *(u32x4*)(cur.dst + (size_t)map_col(gn, cur.mode) * cur.K + cur.kt * 64 + k8) = pack8(f); } }
;         __syncthreads();
;         t = tn;
.Lcv_ld_1:
	s_waitcnt lgkmcnt(0)
	s_barrier
	v_add_u32_e32 v172, s27, v162
	v_mov_b32_e32 v181, v165
	v_min_u32_e32 v181, s77, v181
	v_lshl_add_u32 v173, v181, 2, v172
	v_add_u32_e32 v182, 64, v165
	v_min_u32_e32 v182, s77, v182
	v_lshl_add_u32 v174, v182, 2, v172
	v_add_u32_e32 v183, 128, v165
	v_min_u32_e32 v183, s77, v183
	v_lshl_add_u32 v175, v183, 2, v172
	v_add_u32_e32 v184, 192, v165
	v_min_u32_e32 v184, s77, v184
	v_lshl_add_u32 v176, v184, 2, v172
	ds_read_b32 v120, v173 offset:0
	ds_read_b32 v121, v173 offset:1028
	ds_read_b32 v122, v173 offset:2056
	ds_read_b32 v123, v173 offset:3084
	ds_read_b32 v124, v173 offset:4112
	ds_read_b32 v125, v173 offset:5140
	ds_read_b32 v126, v173 offset:6168
	ds_read_b32 v127, v173 offset:7196
	ds_read_b32 v128, v174 offset:0
	ds_read_b32 v129, v174 offset:1028
	ds_read_b32 v130, v174 offset:2056
	ds_read_b32 v131, v174 offset:3084
	ds_read_b32 v132, v174 offset:4112
	ds_read_b32 v133, v174 offset:5140
	ds_read_b32 v134, v174 offset:6168
	ds_read_b32 v135, v174 offset:7196
	ds_read_b32 v136, v175 offset:0
	ds_read_b32 v137, v175 offset:1028
	ds_read_b32 v138, v175 offset:2056
	ds_read_b32 v139, v175 offset:3084
	ds_read_b32 v140, v175 offset:4112
	ds_read_b32 v141, v175 offset:5140
	ds_read_b32 v142, v175 offset:6168
	ds_read_b32 v143, v175 offset:7196
	ds_read_b32 v144, v176 offset:0
	ds_read_b32 v145, v176 offset:1028
	ds_read_b32 v146, v176 offset:2056
	ds_read_b32 v147, v176 offset:3084
	ds_read_b32 v148, v176 offset:4112
	ds_read_b32 v149, v176 offset:5140
	ds_read_b32 v150, v176 offset:6168
	ds_read_b32 v151, v176 offset:7196
	s_cmp_eq_u32 s75, 0
	s_cbranch_scc0 .Lcv_perm_1
	v_add_u32_e32 v177, s76, v181
	v_add_u32_e32 v178, s76, v182
	v_add_u32_e32 v179, s76, v183
	v_add_u32_e32 v180, s76, v184
.Lcv_permback_1:
	v_lshlrev_b32_e32 v177, s74, v177
	v_add_u32_e32 v177, v177, v163
	v_lshlrev_b32_e32 v178, s74, v178
	v_add_u32_e32 v178, v178, v163
	v_lshlrev_b32_e32 v179, s74, v179
	v_add_u32_e32 v179, v179, v163
	v_lshlrev_b32_e32 v180, s74, v180
	v_add_u32_e32 v180, v180, v163
	s_cmp_eq_u32 s78, 0
	s_cbranch_scc1 .Lcv_nogk_1
	s_waitcnt lgkmcnt(0)
	v_mul_f32_e32 v120, v120, v104
	v_mul_f32_e32 v121, v121, v105
	v_mul_f32_e32 v122, v122, v106
	v_mul_f32_e32 v123, v123, v107
	v_mul_f32_e32 v124, v124, v108
	v_mul_f32_e32 v125, v125, v109
	v_mul_f32_e32 v126, v126, v110
	v_mul_f32_e32 v127, v127, v111
	v_mul_f32_e32 v128, v128, v104
	v_mul_f32_e32 v129, v129, v105
	v_mul_f32_e32 v130, v130, v106
	v_mul_f32_e32 v131, v131, v107
	v_mul_f32_e32 v132, v132, v108
	v_mul_f32_e32 v133, v133, v109
	v_mul_f32_e32 v134, v134, v110
	v_mul_f32_e32 v135, v135, v111
	v_mul_f32_e32 v136, v136, v104
	v_mul_f32_e32 v137, v137, v105
	v_mul_f32_e32 v138, v138, v106
	v_mul_f32_e32 v139, v139, v107
	v_mul_f32_e32 v140, v140, v108
	v_mul_f32_e32 v141, v141, v109
	v_mul_f32_e32 v142, v142, v110
	v_mul_f32_e32 v143, v143, v111
	v_mul_f32_e32 v144, v144, v104
	v_mul_f32_e32 v145, v145, v105
	v_mul_f32_e32 v146, v146, v106
	v_mul_f32_e32 v147, v147, v107
	v_mul_f32_e32 v148, v148, v108
	v_mul_f32_e32 v149, v149, v109
	v_mul_f32_e32 v150, v150, v110
	v_mul_f32_e32 v151, v151, v111
.Lcv_nogk_1:
	s_waitcnt lgkmcnt(0)
	v_cvt_pk_bf16_f32 v152, v120, v121
	v_cvt_pk_bf16_f32 v153, v122, v123
	v_cvt_pk_bf16_f32 v154, v124, v125
	v_cvt_pk_bf16_f32 v155, v126, v127
	global_store_dwordx4 v177, v[152:155], s[72:73]
	s_nop 1
	v_cvt_pk_bf16_f32 v152, v128, v129
	v_cvt_pk_bf16_f32 v153, v130, v131
	v_cvt_pk_bf16_f32 v154, v132, v133
	v_cvt_pk_bf16_f32 v155, v134, v135
	global_store_dwordx4 v178, v[152:155], s[72:73]
	s_nop 1
	v_cvt_pk_bf16_f32 v152, v136, v137
	v_cvt_pk_bf16_f32 v153, v138, v139
	v_cvt_pk_bf16_f32 v154, v140, v141
	v_cvt_pk_bf16_f32 v155, v142, v143
	global_store_dwordx4 v179, v[152:155], s[72:73]
	s_nop 1
	v_cvt_pk_bf16_f32 v152, v144, v145
	v_cvt_pk_bf16_f32 v153, v146, v147
	v_cvt_pk_bf16_f32 v154, v148, v149
	v_cvt_pk_bf16_f32 v155, v150, v151
	global_store_dwordx4 v180, v[152:155], s[72:73]
	s_cmp_eq_u32 s29, 0
	s_cbranch_scc0 .Lcv_nog_1
	global_load_dwordx4 v[104:107], v164, s[38:39]
	global_load_dwordx4 v[108:111], v164, s[38:39] offset:16
	s_mov_b32 s72, s40
	s_mov_b32 s73, s41
	s_mov_b32 s74, s42
	s_mov_b32 s75, s43
	s_mov_b32 s76, s44
	s_mov_b32 s77, s45
	s_mov_b32 s78, s46

; __device__ __forceinline__ CvtTile cvt_get(const Params& p, int t) {
;     const int l = t / TILES_L; int r = t % TILES_L; unsigned char* Wl = p.ws + OFF_W + (size_t)l * SZ_WL; CvtTile c; int nT; c.mode = 0; c.gk = nullptr;
;     if (r < 576) { c.W = p.w_in + (size_t)l * DM * NPROJ; c.K = DM; c.N = NPROJ; nT = 18; c.dst = (bf16_t*)(Wl + WO_IN); c.gk = p.g_mix + l * DM; }
;     else if ((r -= 576) < 48) { c.W = p.w_q_up + (size_t)l * 512 * 1536; c.K = 512; c.N = 1536; nT = 6; c.mode = 1; c.dst = (bf16_t*)(Wl + WO_Q); }
;     else if ((r -= 48) < 32) { c.W = p.w_kv_up + (size_t)l * 256 * 2048; c.K = 256; c.N = 2048; nT = 8; c.mode = 2; c.dst = (bf16_t*)(Wl + WO_KV); }
;     else if ((r -= 32) < 256) { c.W = p.w_out + (size_t)l * DM * DM; c.K = DM; c.N = DM; nT = 8; c.dst = (bf16_t*)(Wl + WO_OUT); }
;     else if ((r -= 256) < 1024) { c.W = p.w_ff1 + (size_t)l * DM * DFF; c.K = DM; c.N = DFF; nT = 32; c.dst = (bf16_t*)(Wl + WO_1); c.gk = p.g_ffn + l * DM; }
;     else { r -= 1024; c.W = p.w_ff2 + (size_t)l * DFF * DM; c.K = DFF; c.N = DM; nT = 8; c.dst = (bf16_t*)(Wl + WO_2); }
;     c.kt = r / nT; c.nt = r % nT; return c;
; __device__ __forceinline__ void convert_phase(const Params& p, LAS unsigned char* lds) {
;     ...
;     while (t < NLAYER * TILES_L) {
; #pragma unroll
;         for (int i = 0; i < 8; ++i) { const int k = (tid >> 6) + 8 * i, n4 = (tid & 63) * 4;
;             T[k * 257 + n4] = v[i][0]; T[k * 257 + n4 + 1] = v[i][1]; T[k * 257 + n4 + 2] = v[i][2]; T[k * 257 + n4 + 3] = v[i][3]; }
;         __syncthreads();
;         const CvtTile cur = c; const int tn = t + G;
;         if (tn < NLAYER * TILES_L) { c = cvt_get(p, tn); cvt_load(c, v, tid); }
.Lcv_w1_2:
	v_add_u32_e32 v171, s27, v161
	ds_write_b32 v171, v64 offset:0
	ds_write_b32 v171, v65 offset:4
	ds_write_b32 v171, v66 offset:8
	ds_write_b32 v171, v67 offset:12
	ds_write_b32 v171, v68 offset:1028
	ds_write_b32 v171, v69 offset:1032
	ds_write_b32 v171, v70 offset:1036
	ds_write_b32 v171, v71 offset:1040
	ds_write_b32 v171, v72 offset:2056
	ds_write_b32 v171, v73 offset:2060
	ds_write_b32 v171, v74 offset:2064
	ds_write_b32 v171, v75 offset:2068
	ds_write_b32 v171, v76 offset:3084
	ds_write_b32 v171, v77 offset:3088
	ds_write_b32 v171, v78 offset:3092
	ds_write_b32 v171, v79 offset:3096
	ds_write_b32 v171, v80 offset:4112
	ds_write_b32 v171, v81 offset:4116
	ds_write_b32 v171, v82 offset:4120
	ds_write_b32 v171, v83 offset:4124
	ds_write_b32 v171, v84 offset:5140
	ds_write_b32 v171, v85 offset:5144
	ds_write_b32 v171, v86 offset:5148
	ds_write_b32 v171, v87 offset:5152
	ds_write_b32 v171, v88 offset:6168
	ds_write_b32 v171, v89 offset:6172
	ds_write_b32 v171, v90 offset:6176
	ds_write_b32 v171, v91 offset:6180
	ds_write_b32 v171, v92 offset:7196
	ds_write_b32 v171, v93 offset:7200
	ds_write_b32 v171, v94 offset:7204
	ds_write_b32 v171, v95 offset:7208
	s_cmp_lt_u32 s26, 11840
	s_cbranch_scc0 .Lcv_nold_2
	s_mov_b32 s0, 0
	s_cmp_ge_u32 s26, 2960
	s_addc_u32 s0, s0, 0
	s_cmp_ge_u32 s26, 5920
	s_addc_u32 s0, s0, 0
	s_cmp_ge_u32 s26, 8880
	s_addc_u32 s0, s0, 0
	s_mul_i32 s1, s0, 2960
	s_sub_u32 s1, s26, s1
	s_mul_i32 s2, s0, 0x5c80000
	s_cmp_lt_u32 s1, 576
	s_cbranch_scc0 .Lcv_d2_w_in_skip
	s_mul_i32 s3, s1, 3641
	s_lshr_b32 s3, s3, 16
	s_mul_i32 s4, s3, 18
	s_sub_u32 s4, s1, s4
	v_readlane_b32 s6, v253, 8
	v_readlane_b32 s7, v253, 9
	s_mul_i32 s5, s0, 0x22a0000
	s_mul_i32 s8, s3, 0x115000
	s_lshl_b32 s9, s4, 10
	s_add_u32 s5, s5, s8
	s_add_u32 s5, s5, s9
	s_add_u32 s34, s6, s5
	s_addc_u32 s35, s7, 0
	s_mov_b32 s36, 0x4540
	s_lshl_b32 s9, s4, 8
	s_mov_b32 s44, s9
	s_sub_u32 s10, 4428, s9
	s_lshl_b32 s37, s10, 2
	s_sub_u32 s45, 4431, s9
	s_add_u32 s5, s2, 0x0
	s_lshl_b32 s8, s3, 7
	s_add_u32 s5, s5, s8
	s_add_u32 s40, s30, s5
	s_addc_u32 s41, s31, 0
	s_mov_b32 s42, 12
	s_mov_b32 s43, 0
	v_readlane_b32 s6, v253, 6
	v_readlane_b32 s7, v253, 7
	s_lshl_b32 s5, s0, 13
	s_lshl_b32 s8, s3, 8
	s_add_u32 s5, s5, s8
	s_add_u32 s38, s6, s5
	s_addc_u32 s39, s7, 0
	s_mov_b32 s46, 1
	s_branch .Lcv_d2_done

; __device__ __forceinline__ void cvt_load(const CvtTile& c, f32x4 (&v)[8], int tid) {
; #pragma unroll
;     for (int i = 0; i < 8; ++i) { const int k = (tid >> 6) + 8 * i, gn = c.nt * 256 + (tid & 63) * 4;
;         v[i] = (f32x4){0.f, 0.f, 0.f, 0.f};
;         if (gn < c.N) { v[i] = __builtin_nontemporal_load((const f32x4*)(c.W + (size_t)(c.kt * 64 + k) * c.N + gn)); if (c.gk) v[i] = v[i] * c.gk[c.kt * 64 + k]; } }
; }
.Lcv_d2_done:
	s_mul_i32 s0, s28, s36
	s_lshl_b32 s0, s0, 3
	v_min_u32_e32 v166, s37, v160
	v_add_u32_e32 v166, s0, v166
	global_load_dwordx4 v[64:67], v166, s[34:35] nt
	v_add_u32_e32 v166, s36, v166
	global_load_dwordx4 v[68:71], v166, s[34:35] nt
	v_add_u32_e32 v166, s36, v166
	global_load_dwordx4 v[72:75], v166, s[34:35] nt
	v_add_u32_e32 v166, s36, v166
	global_load_dwordx4 v[76:79], v166, s[34:35] nt
	v_add_u32_e32 v166, s36, v166
	global_load_dwordx4 v[80:83], v166, s[34:35] nt
	v_add_u32_e32 v166, s36, v166
	global_load_dwordx4 v[84:87], v166, s[34:35] nt
	v_add_u32_e32 v166, s36, v166
	global_load_dwordx4 v[88:91], v166, s[34:35] nt
	v_add_u32_e32 v166, s36, v166
	global_load_dwordx4 v[92:95], v166, s[34:35] nt
	s_branch .Lcv_ld_2

; __device__ __forceinline__ u32x4 pack8(const float* f) { u32x4 w; w.x = cvt_pk_bf16(f[0], f[1]); w.y = cvt_pk_bf16(f[2], f[3]); w.z = cvt_pk_bf16(f[4], f[5]); w.w = cvt_pk_bf16(f[6], f[7]); return w; }
; __device__ __forceinline__ int map_col(int n, int mode) {
;     if (mode == 1) { const int h = n / 192, d = n % 192; if (d < 128) return h * 128 + d; const int jj = d - 128; return 1024 + h * 64 + 2 * (jj & 31) + (jj >> 5); }
;     if (mode == 2) { const int h = n >> 8, d = n & 255; return d < 128 ? h * 128 + d : 1024 + h * 128 + (d - 128); }
;     return n;
; }
; __device__ __forceinline__ void convert_phase(const Params& p, LAS unsigned char* lds) {
;     ...
;         __syncthreads();
;         const CvtTile cur = c; const int tn = t + G;
;         if (tn < NLAYER * TILES_L) { c = cvt_get(p, tn); cvt_load(c, v, tid); }
; #pragma unroll
;         for (int i = 0; i < 4; ++i) { const int ch = tid + 512 * i, n = ch >> 3, k8 = (ch & 7) * 8, gn = cur.nt * 256 + n;
;             if (gn < cur.N) { float f[8];
; #pragma unroll
;                 for (int j = 0; j < 8; ++j) f[j] = T[(k8 + j) * 257 + n];
;                 *(u32x4*)(cur.dst + (size_t)map_col(gn, cur.mode) * cur.K + cur.kt * 64 + k8) = pack8(f); } }
;         __syncthreads();
;         t = tn;
.Lcv_ld_2:
	s_waitcnt lgkmcnt(0)
	s_barrier
	v_add_u32_e32 v172, s27, v162
	v_mov_b32_e32 v181, v165
	v_min_u32_e32 v181, s47, v181
	v_lshl_add_u32 v173, v181, 2, v172
	v_add_u32_e32 v182, 64, v165
	v_min_u32_e32 v182, s47, v182
	v_lshl_add_u32 v174, v182, 2, v172
	v_add_u32_e32 v183, 128, v165
	v_min_u32_e32 v183, s47, v183
	v_lshl_add_u32 v175, v183, 2, v172
	v_add_u32_e32 v184, 192, v165
	v_min_u32_e32 v184, s47, v184
	v_lshl_add_u32 v176, v184, 2, v172
	ds_read_b32 v120, v173 offset:0
	ds_read_b32 v121, v173 offset:1028
	ds_read_b32 v122, v173 offset:2056
	ds_read_b32 v123, v173 offset:3084
	ds_read_b32 v124, v173 offset:4112
	ds_read_b32 v125, v173 offset:5140
	ds_read_b32 v126, v173 offset:6168
	ds_read_b32 v127, v173 offset:7196
	ds_read_b32 v128, v174 offset:0
	ds_read_b32 v129, v174 offset:1028
	ds_read_b32 v130, v174 offset:2056
	ds_read_b32 v131, v174 offset:3084
	ds_read_b32 v132, v174 offset:4112
	ds_read_b32 v133, v174 offset:5140
	ds_read_b32 v134, v174 offset:6168
	ds_read_b32 v135, v174 offset:7196
	ds_read_b32 v136, v175 offset:0
	ds_read_b32 v137, v175 offset:1028
	ds_read_b32 v138, v175 offset:2056
	ds_read_b32 v139, v175 offset:3084
	ds_read_b32 v140, v175 offset:4112
	ds_read_b32 v141, v175 offset:5140
	ds_read_b32 v142, v175 offset:6168
	ds_read_b32 v143, v175 offset:7196
	ds_read_b32 v144, v176 offset:0
	ds_read_b32 v145, v176 offset:1028
	ds_read_b32 v146, v176 offset:2056
	ds_read_b32 v147, v176 offset:3084
	ds_read_b32 v148, v176 offset:4112
	ds_read_b32 v149, v176 offset:5140
	ds_read_b32 v150, v176 offset:6168
	ds_read_b32 v151, v176 offset:7196
	s_cmp_eq_u32 s51, 0
	s_cbranch_scc0 .Lcv_perm_2
	v_add_u32_e32 v177, s52, v181
	v_add_u32_e32 v178, s52, v182
	v_add_u32_e32 v179, s52, v183
	v_add_u32_e32 v180, s52, v184
.Lcv_permback_2:
	v_lshlrev_b32_e32 v177, s50, v177
	v_add_u32_e32 v177, v177, v163
	v_lshlrev_b32_e32 v178, s50, v178
	v_add_u32_e32 v178, v178, v163
	v_lshlrev_b32_e32 v179, s50, v179
	v_add_u32_e32 v179, v179, v163
	v_lshlrev_b32_e32 v180, s50, v180
	v_add_u32_e32 v180, v180, v163
	s_cmp_eq_u32 s33, 0
	s_cbranch_scc1 .Lcv_nogk_2
	s_waitcnt lgkmcnt(0)
	v_mul_f32_e32 v120, v120, v112
	v_mul_f32_e32 v121, v121, v113
	v_mul_f32_e32 v122, v122, v114
	v_mul_f32_e32 v123, v123, v115
	v_mul_f32_e32 v124, v124, v116
	v_mul_f32_e32 v125, v125, v117
	v_mul_f32_e32 v126, v126, v118
	v_mul_f32_e32 v127, v127, v119
	v_mul_f32_e32 v128, v128, v112
	v_mul_f32_e32 v129, v129, v113
	v_mul_f32_e32 v130, v130, v114
	v_mul_f32_e32 v131, v131, v115
	v_mul_f32_e32 v132, v132, v116
	v_mul_f32_e32 v133, v133, v117
	v_mul_f32_e32 v134, v134, v118
	v_mul_f32_e32 v135, v135, v119
	v_mul_f32_e32 v136, v136, v112
	v_mul_f32_e32 v137, v137, v113
	v_mul_f32_e32 v138, v138, v114
	v_mul_f32_e32 v139, v139, v115
	v_mul_f32_e32 v140, v140, v116
	v_mul_f32_e32 v141, v141, v117
	v_mul_f32_e32 v142, v142, v118
	v_mul_f32_e32 v143, v143, v119
	v_mul_f32_e32 v144, v144, v112
	v_mul_f32_e32 v145, v145, v113
	v_mul_f32_e32 v146, v146, v114
	v_mul_f32_e32 v147, v147, v115
	v_mul_f32_e32 v148, v148, v116
	v_mul_f32_e32 v149, v149, v117
	v_mul_f32_e32 v150, v150, v118
	v_mul_f32_e32 v151, v151, v119
.Lcv_nogk_2:
	s_waitcnt lgkmcnt(0)
	v_cvt_pk_bf16_f32 v152, v120, v121
	v_cvt_pk_bf16_f32 v153, v122, v123
	v_cvt_pk_bf16_f32 v154, v124, v125
	v_cvt_pk_bf16_f32 v155, v126, v127
	global_store_dwordx4 v177, v[152:155], s[48:49]
	s_nop 1
	v_cvt_pk_bf16_f32 v152, v128, v129
	v_cvt_pk_bf16_f32 v153, v130, v131
	v_cvt_pk_bf16_f32 v154, v132, v133
	v_cvt_pk_bf16_f32 v155, v134, v135
	global_store_dwordx4 v178, v[152:155], s[48:49]
	s_nop 1
	v_cvt_pk_bf16_f32 v152, v136, v137
	v_cvt_pk_bf16_f32 v153, v138, v139
	v_cvt_pk_bf16_f32 v154, v140, v141
	v_cvt_pk_bf16_f32 v155, v142, v143
	global_store_dwordx4 v179, v[152:155], s[48:49]
	s_nop 1
	v_cvt_pk_bf16_f32 v152, v144, v145
	v_cvt_pk_bf16_f32 v153, v146, v147
	v_cvt_pk_bf16_f32 v154, v148, v149
	v_cvt_pk_bf16_f32 v155, v150, v151
	global_store_dwordx4 v180, v[152:155], s[48:49]
	s_cmp_eq_u32 s29, 0
	s_cbranch_scc0 .Lcv_nog_2
	global_load_dwordx4 v[112:115], v164, s[38:39]
	global_load_dwordx4 v[116:119], v164, s[38:39] offset:16
	s_mov_b32 s48, s40
	s_mov_b32 s49, s41
	s_mov_b32 s50, s42
	s_mov_b32 s51, s43
	s_mov_b32 s52, s44
	s_mov_b32 s47, s45
	s_mov_b32 s33, s46
.Lcv_nog_2:
	s_add_u32 s26, s26, s25
	s_xor_b32 s27, s27, 65792
	s_mul_i32 s0, s25, 3
	s_sub_u32 s0, s26, s0
	s_cmp_lt_u32 s0, 11840
	s_cbranch_scc0 .Lcv_exit
	s_branch .Lcv_loop
.Lcv_perm_0:
	s_cmp_eq_u32 s67, 2
	s_cbranch_scc0 .Lcv_perm1_0
	s_lshr_b32 s0, s68, 1
	v_and_b32_e32 v167, 127, v181
	v_lshrrev_b32_e32 v168, 7, v181
	v_lshl_add_u32 v167, v168, 10, v167
	v_add_u32_e32 v177, s0, v167
	v_and_b32_e32 v167, 127, v182
	v_lshrrev_b32_e32 v168, 7, v182
	v_lshl_add_u32 v167, v168, 10, v167
	v_add_u32_e32 v178, s0, v167
	v_and_b32_e32 v167, 127, v183
	v_lshrrev_b32_e32 v168, 7, v183
	v_lshl_add_u32 v167, v168, 10, v167
	v_add_u32_e32 v179, s0, v167
	v_and_b32_e32 v167, 127, v184
	v_lshrrev_b32_e32 v168, 7, v184
	v_lshl_add_u32 v167, v168, 10, v167
	v_add_u32_e32 v180, s0, v167
	s_branch .Lcv_permback_0
; __device__ __forceinline__ int map_col(int n, int mode) {
;     if (mode == 1) { const int h = n / 192, d = n % 192; if (d < 128) return h * 128 + d; const int jj = d - 128; return 1024 + h * 64 + 2 * (jj & 31) + (jj >> 5); }
;     if (mode == 2) { const int h = n >> 8, d = n & 255; return d < 128 ? h * 128 + d : 1024 + h * 128 + (d - 128); }
;     return n;
; }
.Lcv_perm1_0:
	v_add_u32_e32 v167, s68, v181
	v_lshrrev_b32_e32 v168, 6, v167
	v_mul_u32_u24_e32 v168, 43, v168
	v_lshrrev_b32_e32 v168, 7, v168
	v_mul_u32_u24_e32 v169, 192, v168
	v_sub_u32_e32 v169, v167, v169
	v_lshl_add_u32 v170, v168, 7, v169
	v_add_u32_e32 v167, 0xffffff80, v169
	v_and_b32_e32 v177, 31, v167
	v_lshlrev_b32_e32 v177, 1, v177
	v_lshrrev_b32_e32 v167, 5, v167
	v_and_b32_e32 v167, 1, v167
	v_add_u32_e32 v177, v177, v167
	v_lshl_add_u32 v177, v168, 6, v177
	v_add_u32_e32 v177, 0x400, v177
	v_cmp_gt_u32_e32 vcc, 128, v169
	s_nop 1
	v_cndmask_b32_e32 v177, v177, v170, vcc
	v_add_u32_e32 v167, s68, v182
	v_lshrrev_b32_e32 v168, 6, v167
	v_mul_u32_u24_e32 v168, 43, v168
	v_lshrrev_b32_e32 v168, 7, v168
	v_mul_u32_u24_e32 v169, 192, v168
	v_sub_u32_e32 v169, v167, v169
	v_lshl_add_u32 v170, v168, 7, v169
	v_add_u32_e32 v167, 0xffffff80, v169
	v_and_b32_e32 v178, 31, v167
	v_lshlrev_b32_e32 v178, 1, v178
	v_lshrrev_b32_e32 v167, 5, v167
	v_and_b32_e32 v167, 1, v167
	v_add_u32_e32 v178, v178, v167
	v_lshl_add_u32 v178, v168, 6, v178
	v_add_u32_e32 v178, 0x400, v178
	v_cmp_gt_u32_e32 vcc, 128, v169
	s_nop 1
	v_cndmask_b32_e32 v178, v178, v170, vcc
	v_add_u32_e32 v167, s68, v183
	v_lshrrev_b32_e32 v168, 6, v167
	v_mul_u32_u24_e32 v168, 43, v168
	v_lshrrev_b32_e32 v168, 7, v168
	v_mul_u32_u24_e32 v169, 192, v168
	v_sub_u32_e32 v169, v167, v169
	v_lshl_add_u32 v170, v168, 7, v169
	v_add_u32_e32 v167, 0xffffff80, v169
	v_and_b32_e32 v179, 31, v167
	v_lshlrev_b32_e32 v179, 1, v179
	v_lshrrev_b32_e32 v167, 5, v167
	v_and_b32_e32 v167, 1, v167
	v_add_u32_e32 v179, v179, v167
	v_lshl_add_u32 v179, v168, 6, v179
	v_add_u32_e32 v179, 0x400, v179
	v_cmp_gt_u32_e32 vcc, 128, v169
	s_nop 1
	v_cndmask_b32_e32 v179, v179, v170, vcc
	v_add_u32_e32 v167, s68, v184
	v_lshrrev_b32_e32 v168, 6, v167
	v_mul_u32_u24_e32 v168, 43, v168
	v_lshrrev_b32_e32 v168, 7, v168
	v_mul_u32_u24_e32 v169, 192, v168
	v_sub_u32_e32 v169, v167, v169
	v_lshl_add_u32 v170, v168, 7, v169
	v_add_u32_e32 v167, 0xffffff80, v169
	v_and_b32_e32 v180, 31, v167
	v_lshlrev_b32_e32 v180, 1, v180
	v_lshrrev_b32_e32 v167, 5, v167
	v_and_b32_e32 v167, 1, v167
	v_add_u32_e32 v180, v180, v167
	v_lshl_add_u32 v180, v168, 6, v180
	v_add_u32_e32 v180, 0x400, v180
	v_cmp_gt_u32_e32 vcc, 128, v169
	s_nop 1
	v_cndmask_b32_e32 v180, v180, v170, vcc
	s_branch .Lcv_permback_0
.Lcv_perm_1:
	s_cmp_eq_u32 s75, 2
	s_cbranch_scc0 .Lcv_perm1_1
	s_lshr_b32 s0, s76, 1
	v_and_b32_e32 v167, 127, v181
	v_lshrrev_b32_e32 v168, 7, v181
	v_lshl_add_u32 v167, v168, 10, v167
	v_add_u32_e32 v177, s0, v167
	v_and_b32_e32 v167, 127, v182
	v_lshrrev_b32_e32 v168, 7, v182
	v_lshl_add_u32 v167, v168, 10, v167
	v_add_u32_e32 v178, s0, v167
	v_and_b32_e32 v167, 127, v183
	v_lshrrev_b32_e32 v168, 7, v183
	v_lshl_add_u32 v167, v168, 10, v167
	v_add_u32_e32 v179, s0, v167
	v_and_b32_e32 v167, 127, v184
	v_lshrrev_b32_e32 v168, 7, v184
	v_lshl_add_u32 v167, v168, 10, v167
	v_add_u32_e32 v180, s0, v167
	s_branch .Lcv_permback_1
.Lcv_perm1_1:
	v_add_u32_e32 v167, s76, v181
	v_lshrrev_b32_e32 v168, 6, v167
	v_mul_u32_u24_e32 v168, 43, v168
	v_lshrrev_b32_e32 v168, 7, v168
	v_mul_u32_u24_e32 v169, 192, v168
	v_sub_u32_e32 v169, v167, v169
	v_lshl_add_u32 v170, v168, 7, v169
	v_add_u32_e32 v167, 0xffffff80, v169
	v_and_b32_e32 v177, 31, v167
	v_lshlrev_b32_e32 v177, 1, v177
	v_lshrrev_b32_e32 v167, 5, v167
	v_and_b32_e32 v167, 1, v167
	v_add_u32_e32 v177, v177, v167
	v_lshl_add_u32 v177, v168, 6, v177
	v_add_u32_e32 v177, 0x400, v177
	v_cmp_gt_u32_e32 vcc, 128, v169
	s_nop 1
	v_cndmask_b32_e32 v177, v177, v170, vcc
	v_add_u32_e32 v167, s76, v182
	v_lshrrev_b32_e32 v168, 6, v167
	v_mul_u32_u24_e32 v168, 43, v168
	v_lshrrev_b32_e32 v168, 7, v168
	v_mul_u32_u24_e32 v169, 192, v168
	v_sub_u32_e32 v169, v167, v169
	v_lshl_add_u32 v170, v168, 7, v169
	v_add_u32_e32 v167, 0xffffff80, v169
	v_and_b32_e32 v178, 31, v167
	v_lshlrev_b32_e32 v178, 1, v178
	v_lshrrev_b32_e32 v167, 5, v167
	v_and_b32_e32 v167, 1, v167
	v_add_u32_e32 v178, v178, v167
	v_lshl_add_u32 v178, v168, 6, v178
	v_add_u32_e32 v178, 0x400, v178
	v_cmp_gt_u32_e32 vcc, 128, v169
	s_nop 1
	v_cndmask_b32_e32 v178, v178, v170, vcc
	v_add_u32_e32 v167, s76, v183
	v_lshrrev_b32_e32 v168, 6, v167
	v_mul_u32_u24_e32 v168, 43, v168
	v_lshrrev_b32_e32 v168, 7, v168
	v_mul_u32_u24_e32 v169, 192, v168
	v_sub_u32_e32 v169, v167, v169
	v_lshl_add_u32 v170, v168, 7, v169
	v_add_u32_e32 v167, 0xffffff80, v169
	v_and_b32_e32 v179, 31, v167
	v_lshlrev_b32_e32 v179, 1, v179
	v_lshrrev_b32_e32 v167, 5, v167
	v_and_b32_e32 v167, 1, v167
	v_add_u32_e32 v179, v179, v167
	v_lshl_add_u32 v179, v168, 6, v179
	v_add_u32_e32 v179, 0x400, v179
	v_cmp_gt_u32_e32 vcc, 128, v169
	s_nop 1
	v_cndmask_b32_e32 v179, v179, v170, vcc
	v_add_u32_e32 v167, s76, v184
	v_lshrrev_b32_e32 v168, 6, v167
	v_mul_u32_u24_e32 v168, 43, v168
	v_lshrrev_b32_e32 v168, 7, v168
	v_mul_u32_u24_e32 v169, 192, v168
	v_sub_u32_e32 v169, v167, v169
	v_lshl_add_u32 v170, v168, 7, v169
	v_add_u32_e32 v167, 0xffffff80, v169
	v_and_b32_e32 v180, 31, v167
	v_lshlrev_b32_e32 v180, 1, v180
	v_lshrrev_b32_e32 v167, 5, v167
	v_and_b32_e32 v167, 1, v167
	v_add_u32_e32 v180, v180, v167
	v_lshl_add_u32 v180, v168, 6, v180
	v_add_u32_e32 v180, 0x400, v180
	v_cmp_gt_u32_e32 vcc, 128, v169
	s_nop 1
	v_cndmask_b32_e32 v180, v180, v170, vcc
	s_branch .Lcv_permback_1
; __device__ __forceinline__ int lbid() { int t = blockIdx.x; asm volatile("" : "+s"(t)); return t; }
; __device__ __forceinline__ int map_col(int n, int mode) {
;     if (mode == 1) { const int h = n / 192, d = n % 192; if (d < 128) return h * 128 + d; const int jj = d - 128; return 1024 + h * 64 + 2 * (jj & 31) + (jj >> 5); }
;     if (mode == 2) { const int h = n >> 8, d = n & 255; return d < 128 ? h * 128 + d : 1024 + h * 128 + (d - 128); }
;     return n;
; }
; __device__ __forceinline__ void convert_phase(const Params& p, LAS unsigned char* lds) {
;     ...
;     constexpr int PADV = (NPROJP - NPROJ) * DM * 2 / 16;
;     for (int i = lbid() * 512 + tid; i < NLAYER * PADV; i += G * 512) { const int l = i / PADV, j = i % PADV;
.Lcv_perm_2:
	s_cmp_eq_u32 s51, 2
	s_cbranch_scc0 .Lcv_perm1_2
	s_lshr_b32 s0, s52, 1
	v_and_b32_e32 v167, 127, v181
	v_lshrrev_b32_e32 v168, 7, v181
	v_lshl_add_u32 v167, v168, 10, v167
	v_add_u32_e32 v177, s0, v167
	v_and_b32_e32 v167, 127, v182
	v_lshrrev_b32_e32 v168, 7, v182
	v_lshl_add_u32 v167, v168, 10, v167
	v_add_u32_e32 v178, s0, v167
	v_and_b32_e32 v167, 127, v183
	v_lshrrev_b32_e32 v168, 7, v183
	v_lshl_add_u32 v167, v168, 10, v167
	v_add_u32_e32 v179, s0, v167
	v_and_b32_e32 v167, 127, v184
	v_lshrrev_b32_e32 v168, 7, v184
	v_lshl_add_u32 v167, v168, 10, v167
	v_add_u32_e32 v180, s0, v167
	s_branch .Lcv_permback_2
.Lcv_perm1_2:
	v_add_u32_e32 v167, s52, v181
	v_lshrrev_b32_e32 v168, 6, v167
	v_mul_u32_u24_e32 v168, 43, v168
	v_lshrrev_b32_e32 v168, 7, v168
	v_mul_u32_u24_e32 v169, 192, v168
	v_sub_u32_e32 v169, v167, v169
	v_lshl_add_u32 v170, v168, 7, v169
	v_add_u32_e32 v167, 0xffffff80, v169
	v_and_b32_e32 v177, 31, v167
	v_lshlrev_b32_e32 v177, 1, v177
	v_lshrrev_b32_e32 v167, 5, v167
	v_and_b32_e32 v167, 1, v167
	v_add_u32_e32 v177, v177, v167
	v_lshl_add_u32 v177, v168, 6, v177
	v_add_u32_e32 v177, 0x400, v177
	v_cmp_gt_u32_e32 vcc, 128, v169
	s_nop 1
	v_cndmask_b32_e32 v177, v177, v170, vcc
	v_add_u32_e32 v167, s52, v182
	v_lshrrev_b32_e32 v168, 6, v167
	v_mul_u32_u24_e32 v168, 43, v168
	v_lshrrev_b32_e32 v168, 7, v168
	v_mul_u32_u24_e32 v169, 192, v168
	v_sub_u32_e32 v169, v167, v169
	v_lshl_add_u32 v170, v168, 7, v169
	v_add_u32_e32 v167, 0xffffff80, v169
	v_and_b32_e32 v178, 31, v167
	v_lshlrev_b32_e32 v178, 1, v178
	v_lshrrev_b32_e32 v167, 5, v167
	v_and_b32_e32 v167, 1, v167
	v_add_u32_e32 v178, v178, v167
	v_lshl_add_u32 v178, v168, 6, v178
	v_add_u32_e32 v178, 0x400, v178
	v_cmp_gt_u32_e32 vcc, 128, v169
	s_nop 1
	v_cndmask_b32_e32 v178, v178, v170, vcc
	v_add_u32_e32 v167, s52, v183
	v_lshrrev_b32_e32 v168, 6, v167
	v_mul_u32_u24_e32 v168, 43, v168
	v_lshrrev_b32_e32 v168, 7, v168
	v_mul_u32_u24_e32 v169, 192, v168
	v_sub_u32_e32 v169, v167, v169
	v_lshl_add_u32 v170, v168, 7, v169
	v_add_u32_e32 v167, 0xffffff80, v169
	v_and_b32_e32 v179, 31, v167
	v_lshlrev_b32_e32 v179, 1, v179
	v_lshrrev_b32_e32 v167, 5, v167
	v_and_b32_e32 v167, 1, v167
	v_add_u32_e32 v179, v179, v167
	v_lshl_add_u32 v179, v168, 6, v179
	v_add_u32_e32 v179, 0x400, v179
	v_cmp_gt_u32_e32 vcc, 128, v169
	s_nop 1
	v_cndmask_b32_e32 v179, v179, v170, vcc
	v_add_u32_e32 v167, s52, v184
	v_lshrrev_b32_e32 v168, 6, v167
	v_mul_u32_u24_e32 v168, 43, v168
	v_lshrrev_b32_e32 v168, 7, v168
	v_mul_u32_u24_e32 v169, 192, v168
	v_sub_u32_e32 v169, v167, v169
	v_lshl_add_u32 v170, v168, 7, v169
	v_add_u32_e32 v167, 0xffffff80, v169
	v_and_b32_e32 v180, 31, v167
	v_lshlrev_b32_e32 v180, 1, v180
	v_lshrrev_b32_e32 v167, 5, v167
	v_and_b32_e32 v167, 1, v167
	v_add_u32_e32 v180, v180, v167
	v_lshl_add_u32 v180, v168, 6, v180
	v_add_u32_e32 v180, 0x400, v180
	v_cmp_gt_u32_e32 vcc, 128, v169
	s_nop 1
	v_cndmask_b32_e32 v180, v180, v170, vcc
	s_branch .Lcv_permback_2
.Lcv_exit:
	s_waitcnt vmcnt(0) lgkmcnt(0)
	s_barrier
	v_mov_b32_e32 v40, v192
	v_ashrrev_i32_e32 v36, 6, v40

; __device__ __forceinline__ unsigned cvt_pk_bf16(float lo, float hi) { unsigned r; asm volatile("v_cvt_pk_bf16_f32 %0, %1, %2" : "=v"(r) : "v"(lo), "v"(hi)); return r; }
; __device__ __forceinline__ int lbid() { int t = blockIdx.x; asm volatile("" : "+s"(t)); return t; }
; __device__ __forceinline__ float wave_sum(float v) { for (int o = 32; o > 0; o >>= 1) v += __shfl_xor(v, o); return v; }
; __device__ __forceinline__ void convert_phase(const Params& p, LAS unsigned char* lds) {
;     ...
;     { const int wid = tid >> 6, lane = tid & 63; bf16_t* H = (bf16_t*)(p.ws + OFF_H); unsigned long long* ssqa = (unsigned long long*)(p.ws + OFF_SSQA);
;         for (int row = lbid() * 8 + wid; row < S_; row += G * 8) { const float* xr = p.x + (size_t)row * DM; float ssq = 0.f;
; #pragma unroll
;             for (int i = 0; i < 8; ++i) { const int col = (i * 64 + lane) * 4; const f32x4 x = *(const f32x4*)(xr + col);
;                 ssq += x[0] * x[0] + x[1] * x[1] + x[2] * x[2] + x[3] * x[3];
;                 u32x2 w; w.x = cvt_pk_bf16(x[0], x[1]); w.y = cvt_pk_bf16(x[2], x[3]); *(u32x2*)(H + (size_t)row * DM + col) = w; }
;             ssq = wave_sum(ssq); if (lane == 0) ssqa[row] = (unsigned long long)(ssq * 1048576.f); } }
.LBB0_712:
	v_readlane_b32 s8, v252, 1
	v_readlane_b32 s12, v252, 5
	v_readlane_b32 s13, v252, 6
	s_mov_b32 s0, 0x1b200000
	s_waitcnt lgkmcnt(0)
	global_load_dwordx4 v[8:11], v[6:7], off offset:-4096
	v_lshl_add_u64 v[12:13], s[12:13], 0, v[4:5]
	v_add_co_u32_e64 v40, s[0:1], s0, v12
	s_waitcnt vmcnt(0)
	v_cvt_pk_bf16_f32 v12, v8, v9
	v_and_b32_e32 v1, 64, v238
	v_addc_co_u32_e64 v41, s[0:1], 0, v13, s[0:1]
	v_cvt_pk_bf16_f32 v13, v10, v11
	global_store_dwordx2 v[40:41], v[12:13], off
	global_load_dwordx4 v[12:15], v[6:7], off offset:-3072
	s_waitcnt vmcnt(0)
	v_cvt_pk_bf16_f32 v16, v12, v13
	v_cvt_pk_bf16_f32 v17, v14, v15
	global_store_dwordx2 v[40:41], v[16:17], off offset:512
	global_load_dwordx4 v[16:19], v[6:7], off offset:-2048
	s_waitcnt vmcnt(0)
	v_cvt_pk_bf16_f32 v20, v16, v17
	v_cvt_pk_bf16_f32 v21, v18, v19
	global_store_dwordx2 v[40:41], v[20:21], off offset:1024
	global_load_dwordx4 v[20:23], v[6:7], off offset:-1024
	s_waitcnt vmcnt(0)
	v_cvt_pk_bf16_f32 v24, v20, v21
	v_cvt_pk_bf16_f32 v25, v22, v23
	global_store_dwordx2 v[40:41], v[24:25], off offset:1536
	global_load_dwordx4 v[24:27], v[6:7], off
	s_waitcnt vmcnt(0)
	v_cvt_pk_bf16_f32 v28, v24, v25
	v_cvt_pk_bf16_f32 v29, v26, v27
	global_store_dwordx2 v[40:41], v[28:29], off offset:2048
	global_load_dwordx4 v[28:31], v[6:7], off offset:1024
	s_waitcnt vmcnt(0)
	v_cvt_pk_bf16_f32 v32, v28, v29
	v_cvt_pk_bf16_f32 v33, v30, v31
	global_store_dwordx2 v[40:41], v[32:33], off offset:2560
	global_load_dwordx4 v[32:35], v[6:7], off offset:2048
	s_waitcnt vmcnt(0)
	v_cvt_pk_bf16_f32 v36, v32, v33
	v_cvt_pk_bf16_f32 v37, v34, v35
	global_store_dwordx2 v[40:41], v[36:37], off offset:3072
	global_load_dwordx4 v[36:39], v[6:7], off offset:3072
	v_xor_b32_e32 v42, 32, v238
	v_add_u32_e32 v1, 64, v1
	v_cmp_lt_i32_e64 s[0:1], v42, v1
	v_readlane_b32 s9, v252, 2
	v_readlane_b32 s10, v252, 3
	v_cndmask_b32_e64 v42, v238, v42, s[0:1]
	v_lshlrev_b32_e32 v42, 2, v42
	v_readlane_b32 s11, v252, 4
	v_readlane_b32 s14, v252, 7
	v_readlane_b32 s15, v252, 8
	v_mul_f32_e32 v9, v9, v9
	v_fmac_f32_e32 v9, v8, v8
	v_fmac_f32_e32 v9, v10, v10
	v_fmac_f32_e32 v9, v11, v11
	v_xor_b32_e32 v10, 16, v238
	v_cmp_lt_i32_e64 s[0:1], v10, v1
	v_mul_f32_e32 v8, v13, v13
	v_fmac_f32_e32 v8, v12, v12
	v_fmac_f32_e32 v8, v14, v14
	v_fmac_f32_e32 v8, v15, v15
	v_add_f32_e32 v8, v9, v8
	v_mul_f32_e32 v9, v17, v17
	v_fmac_f32_e32 v9, v16, v16
	v_fmac_f32_e32 v9, v18, v18
	v_fmac_f32_e32 v9, v19, v19
	v_add_f32_e32 v8, v8, v9
	v_mul_f32_e32 v9, v21, v21
	v_fmac_f32_e32 v9, v20, v20
	v_fmac_f32_e32 v9, v22, v22
	v_fmac_f32_e32 v9, v23, v23
	v_add_f32_e32 v8, v8, v9
	v_mul_f32_e32 v9, v25, v25
	v_fmac_f32_e32 v9, v24, v24
	v_fmac_f32_e32 v9, v26, v26
	v_fmac_f32_e32 v9, v27, v27
	v_add_f32_e32 v8, v8, v9
	v_mul_f32_e32 v9, v29, v29
	v_fmac_f32_e32 v9, v28, v28
	v_fmac_f32_e32 v9, v30, v30
	v_fmac_f32_e32 v9, v31, v31
	v_add_f32_e32 v8, v8, v9
	v_mul_f32_e32 v9, v33, v33
	v_fmac_f32_e32 v9, v32, v32
	v_fmac_f32_e32 v9, v34, v34
	v_fmac_f32_e32 v9, v35, v35
	v_add_f32_e32 v8, v8, v9
	s_waitcnt vmcnt(0)
	v_mul_f32_e32 v9, v37, v37
	v_fmac_f32_e32 v9, v36, v36
	v_fmac_f32_e32 v9, v38, v38
	v_fmac_f32_e32 v9, v39, v39
	v_add_f32_e32 v8, v8, v9
	ds_bpermute_b32 v9, v42, v8
	v_cndmask_b32_e64 v10, v238, v10, s[0:1]
	v_lshlrev_b32_e32 v10, 2, v10
	s_waitcnt lgkmcnt(0)
	v_add_f32_e32 v8, v8, v9
	ds_bpermute_b32 v9, v10, v8
	v_xor_b32_e32 v10, 8, v238
	v_cmp_lt_i32_e64 s[0:1], v10, v1
	s_waitcnt lgkmcnt(0)
	v_add_f32_e32 v8, v8, v9
	v_cndmask_b32_e64 v10, v238, v10, s[0:1]
	v_lshlrev_b32_e32 v10, 2, v10
	ds_bpermute_b32 v9, v10, v8
	v_xor_b32_e32 v10, 4, v238
	v_cmp_lt_i32_e64 s[0:1], v10, v1
	s_waitcnt lgkmcnt(0)
	v_add_f32_e32 v8, v8, v9
	v_cndmask_b32_e64 v10, v238, v10, s[0:1]
	v_lshlrev_b32_e32 v10, 2, v10
	ds_bpermute_b32 v9, v10, v8
	v_xor_b32_e32 v10, 2, v238
	v_cmp_lt_i32_e64 s[0:1], v10, v1
	s_waitcnt lgkmcnt(0)
	v_add_f32_e32 v8, v8, v9
	v_cndmask_b32_e64 v10, v238, v10, s[0:1]
	v_lshlrev_b32_e32 v10, 2, v10
	ds_bpermute_b32 v9, v10, v8
	v_xor_b32_e32 v10, 1, v238
	v_cmp_lt_i32_e64 s[0:1], v10, v1
	s_waitcnt lgkmcnt(0)
	v_add_f32_e32 v1, v8, v9
	v_cndmask_b32_e64 v10, v238, v10, s[0:1]
	v_lshlrev_b32_e32 v8, 2, v10
	ds_bpermute_b32 v8, v8, v1
	v_cvt_pk_bf16_f32 v10, v36, v37
	v_cvt_pk_bf16_f32 v11, v38, v39
	global_store_dwordx2 v[40:41], v[10:11], off offset:3584
	s_and_saveexec_b64 s[0:1], vcc
	s_cbranch_execz .LBB0_711
	s_waitcnt lgkmcnt(0)
	v_add_f32_e32 v1, v1, v8
	v_mul_f32_e32 v1, 0x49800000, v1
	v_trunc_f32_e32 v1, v1
	v_mul_f32_e32 v8, 0x2f800000, v1
	v_floor_f32_e32 v9, v8
	v_fmac_f32_e32 v1, 0xcf800000, v9
	v_cvt_u32_f32_e32 v8, v1
	v_cvt_u32_f32_e32 v9, v9
	v_readlane_b32 s8, v252, 1
	v_readlane_b32 s12, v252, 5
	v_readlane_b32 s13, v252, 6
	v_readlane_b32 s9, v252, 2
	v_readlane_b32 s10, v252, 3
	v_lshl_add_u64 v[10:11], s[12:13], 0, v[2:3]
	v_readlane_b32 s11, v252, 4
	v_readlane_b32 s14, v252, 7
	v_readlane_b32 s15, v252, 8
	global_store_dwordx2 v[10:11], v[8:9], off
	s_branch .LBB0_711
.LBB0_715:
	s_endpgm
